# attention KV loop: per-lane K/V pointers formed once per unit, per tile only the wave-uniform row offset is added (5 VALU address ops instead of 15)
# speedup vs baseline: 1.0066x; 1.0049x over previous
.LBB0_562:
	v_mov_b32_e32 v41, v181
	s_add_i32 s7, 0, 0x14000
	v_ashrrev_i32_e32 v0, 6, v41
	v_and_b32_e32 v1, 0x3fffffc0, v41
	s_and_b32 s5, s5, 7
	v_and_b32_e32 v168, 31, v41
	v_lshl_add_u32 v169, v1, 2, s7
	s_movk_i32 s7, 0x1800
	v_lshl_add_u32 v170, v0, 5, s6
	v_mul_lo_u32 v37, v0, s7
	v_add_u32_e32 v36, v170, v168
	v_mov_b64_e32 v[0:1], s[60:61]
	s_mul_i32 s11, s5, 0xc0
	v_bfe_u32 v159, v41, 5, 1
	v_mad_i64_i32 v[0:1], s[6:7], v36, s87, v[0:1]
	s_lshl_b32 s44, s11, 1
	v_lshl_add_u64 v[0:1], v[0:1], 0, s[44:45]
	v_lshlrev_b32_e32 v176, 4, v159
	v_lshl_add_u64 v[4:5], v[0:1], 0, v[176:177]
	global_load_dwordx4 v[42:45], v[4:5], off
	global_load_dwordx4 v[46:49], v[4:5], off offset:32
	global_load_dwordx4 v[50:53], v[4:5], off offset:64
	global_load_dwordx4 v[32:35], v[4:5], off offset:96
	global_load_dwordx4 v[28:31], v[4:5], off offset:128
	global_load_dwordx4 v[24:27], v[4:5], off offset:160
	global_load_dwordx4 v[20:23], v[4:5], off offset:192
	global_load_dwordx4 v[16:19], v[4:5], off offset:224
	global_load_dwordx4 v[8:11], v[4:5], off offset:256
	global_load_dwordx4 v[12:15], v[4:5], off offset:288
	global_load_dwordx4 v[0:3], v[4:5], off offset:320
	s_nop 0
	global_load_dwordx4 v[4:7], v[4:5], off offset:352
	v_and_b32_e32 v66, 63, v41
	s_add_i32 s6, 0, 0x14800
	v_lshlrev_b32_e32 v67, 4, v66
	v_add_u32_e32 v37, s6, v37
	v_add_u32_e32 v171, v37, v67
	s_mov_b64 s[6:7], 0x40040
	v_ashrrev_i32_e32 v148, 4, v41
	s_cmp_lg_u32 0, -1
	s_cselect_b32 s16, 0, 0
	v_ashrrev_i32_e32 v149, 31, v148
	v_lshl_add_u64 v[156:157], v[148:149], 0, 32
	s_mov_b32 s46, s45
	s_mov_b32 s47, s45
	s_mov_b32 s48, s45
	s_mov_b32 s49, s45
	s_mov_b32 s50, s45
	s_mov_b32 s51, s45
	s_mov_b32 s52, s45
	s_mov_b32 s53, s45
	s_mov_b32 s54, s45
	s_mov_b32 s55, s45
	s_mov_b32 s56, s45
	s_mov_b32 s57, s45
	s_mov_b32 s58, s45
	s_mov_b32 s59, s45
	s_mov_b32 s13, 2
	v_lshl_add_u32 v173, v168, 2, v169
	v_mov_b32_e32 v188, 0
	s_waitcnt vmcnt(0)
	v_and_b32_e32 v68, 0xffff0000, v42
	v_and_b32_e32 v70, 0xffff0000, v43
	v_lshlrev_b32_e32 v69, 16, v42
	v_mul_f32_e32 v38, v68, v68
	v_lshlrev_b32_e32 v71, 16, v43
	v_mul_f32_e32 v39, v70, v70
	v_fmac_f32_e32 v38, v69, v69
	v_fmac_f32_e32 v39, v71, v71
	v_and_b32_e32 v72, 0xffff0000, v44
	v_add_f32_e32 v38, v38, v39
	v_lshlrev_b32_e32 v73, 16, v44
	v_mul_f32_e32 v39, v72, v72
	v_fmac_f32_e32 v39, v73, v73
	v_and_b32_e32 v76, 0xffff0000, v45
	v_add_f32_e32 v38, v39, v38
	v_lshlrev_b32_e32 v77, 16, v45
	v_mul_f32_e32 v39, v76, v76
	v_fmac_f32_e32 v39, v77, v77
	v_and_b32_e32 v74, 0xffff0000, v46
	v_add_f32_e32 v38, v39, v38
	v_lshlrev_b32_e32 v75, 16, v46
	v_mul_f32_e32 v39, v74, v74
	v_fmac_f32_e32 v39, v75, v75
	v_and_b32_e32 v78, 0xffff0000, v47
	v_add_f32_e32 v38, v39, v38
	v_lshlrev_b32_e32 v79, 16, v47
	v_mul_f32_e32 v39, v78, v78
	v_fmac_f32_e32 v39, v79, v79
	v_and_b32_e32 v80, 0xffff0000, v48
	v_add_f32_e32 v38, v39, v38
	v_lshlrev_b32_e32 v82, 16, v48
	v_mul_f32_e32 v39, v80, v80
	v_fmac_f32_e32 v39, v82, v82
	v_and_b32_e32 v85, 0xffff0000, v49
	v_add_f32_e32 v38, v39, v38
	v_lshlrev_b32_e32 v86, 16, v49
	v_mul_f32_e32 v39, v85, v85
	v_fmac_f32_e32 v39, v86, v86
	v_and_b32_e32 v83, 0xffff0000, v50
	v_add_f32_e32 v38, v39, v38
	v_lshlrev_b32_e32 v84, 16, v50
	v_mul_f32_e32 v39, v83, v83
	v_fmac_f32_e32 v39, v84, v84
	v_and_b32_e32 v87, 0xffff0000, v51
	v_add_f32_e32 v38, v39, v38
	v_lshlrev_b32_e32 v88, 16, v51
	v_mul_f32_e32 v39, v87, v87
	v_fmac_f32_e32 v39, v88, v88
	v_and_b32_e32 v93, 0xffff0000, v52
	v_add_f32_e32 v38, v39, v38
	v_lshlrev_b32_e32 v95, 16, v52
	v_mul_f32_e32 v39, v93, v93
	v_fmac_f32_e32 v39, v95, v95
	v_and_b32_e32 v104, 0xffff0000, v53
	v_add_f32_e32 v38, v39, v38
	v_lshlrev_b32_e32 v105, 16, v53
	v_mul_f32_e32 v39, v104, v104
	v_and_b32_e32 v91, 0xffff0000, v32
	v_fmac_f32_e32 v39, v105, v105
	v_lshlrev_b32_e32 v108, 16, v32
	v_mul_f32_e32 v32, v91, v91
	v_and_b32_e32 v89, 0xffff0000, v33
	v_add_f32_e32 v38, v39, v38
	v_fmac_f32_e32 v32, v108, v108
	v_lshlrev_b32_e32 v94, 16, v33
	v_mul_f32_e32 v33, v89, v89
	v_add_f32_e32 v32, v32, v38
	v_fmac_f32_e32 v33, v94, v94
	v_and_b32_e32 v110, 0xffff0000, v34
	v_add_f32_e32 v32, v33, v32
	v_lshlrev_b32_e32 v112, 16, v34
	v_mul_f32_e32 v33, v110, v110
	v_fmac_f32_e32 v33, v112, v112
	v_and_b32_e32 v109, 0xffff0000, v35
	v_add_f32_e32 v32, v33, v32
	v_lshlrev_b32_e32 v111, 16, v35
	v_mul_f32_e32 v33, v109, v109
	v_and_b32_e32 v114, 0xffff0000, v28
	v_fmac_f32_e32 v33, v111, v111
	v_lshlrev_b32_e32 v113, 16, v28
	v_mul_f32_e32 v28, v114, v114
	v_and_b32_e32 v130, 0xffff0000, v29
	v_add_f32_e32 v32, v33, v32
	v_fmac_f32_e32 v28, v113, v113
	v_lshlrev_b32_e32 v115, 16, v29
	v_mul_f32_e32 v29, v130, v130
	v_add_f32_e32 v28, v28, v32
	v_fmac_f32_e32 v29, v115, v115
	v_and_b32_e32 v132, 0xffff0000, v30
	v_add_f32_e32 v28, v29, v28
	v_lshlrev_b32_e32 v131, 16, v30
	v_mul_f32_e32 v29, v132, v132
	v_fmac_f32_e32 v29, v131, v131
	v_and_b32_e32 v134, 0xffff0000, v31
	v_add_f32_e32 v28, v29, v28
	v_lshlrev_b32_e32 v133, 16, v31
	v_mul_f32_e32 v29, v134, v134
	v_and_b32_e32 v126, 0xffff0000, v24
	v_fmac_f32_e32 v29, v133, v133
	v_lshlrev_b32_e32 v128, 16, v24
	v_mul_f32_e32 v24, v126, v126
	v_and_b32_e32 v116, 0xffff0000, v25
	v_add_f32_e32 v28, v29, v28
	v_fmac_f32_e32 v24, v128, v128
	v_lshlrev_b32_e32 v118, 16, v25
	v_mul_f32_e32 v25, v116, v116
	v_add_f32_e32 v24, v24, v28
	v_fmac_f32_e32 v25, v118, v118
	v_and_b32_e32 v127, 0xffff0000, v26
	v_add_f32_e32 v24, v25, v24
	v_lshlrev_b32_e32 v129, 16, v26
	v_mul_f32_e32 v25, v127, v127
	v_fmac_f32_e32 v25, v129, v129
	v_and_b32_e32 v117, 0xffff0000, v27
	v_add_f32_e32 v24, v25, v24
	v_lshlrev_b32_e32 v119, 16, v27
	v_mul_f32_e32 v25, v117, v117
	v_and_b32_e32 v122, 0xffff0000, v20
	v_fmac_f32_e32 v25, v119, v119
	v_lshlrev_b32_e32 v124, 16, v20
	v_mul_f32_e32 v20, v122, v122
	v_and_b32_e32 v90, 0xffff0000, v21
	v_add_f32_e32 v24, v25, v24
	v_fmac_f32_e32 v20, v124, v124
	v_lshlrev_b32_e32 v120, 16, v21
	v_mul_f32_e32 v21, v90, v90
	v_add_f32_e32 v20, v20, v24
	v_fmac_f32_e32 v21, v120, v120
	v_and_b32_e32 v123, 0xffff0000, v22
	v_add_f32_e32 v20, v21, v20
	v_lshlrev_b32_e32 v125, 16, v22
	v_mul_f32_e32 v21, v123, v123
	v_fmac_f32_e32 v21, v125, v125
	v_and_b32_e32 v92, 0xffff0000, v23
	v_add_f32_e32 v20, v21, v20
	v_lshlrev_b32_e32 v121, 16, v23
	v_mul_f32_e32 v21, v92, v92
	v_fmac_f32_e32 v21, v121, v121
	v_add_f32_e32 v21, v21, v20
	v_and_b32_e32 v20, 0xffff0000, v16
	v_lshlrev_b32_e32 v22, 16, v16
	v_mul_f32_e32 v16, v20, v20
	v_fmac_f32_e32 v16, v22, v22
	v_add_f32_e32 v23, v16, v21
	v_and_b32_e32 v16, 0xffff0000, v17
	v_lshlrev_b32_e32 v21, 16, v17
	v_mul_f32_e32 v17, v16, v16
	v_fmac_f32_e32 v17, v21, v21
	v_lshlrev_b32_e32 v81, 16, v18
	v_and_b32_e32 v18, 0xffff0000, v18
	v_add_f32_e32 v17, v17, v23
	v_mul_f32_e32 v23, v18, v18
	v_fmac_f32_e32 v23, v81, v81
	v_add_f32_e32 v24, v23, v17
	v_and_b32_e32 v17, 0xffff0000, v19
	v_lshlrev_b32_e32 v23, 16, v19
	v_mul_f32_e32 v19, v17, v17
	v_fmac_f32_e32 v19, v23, v23
	v_add_f32_e32 v19, v19, v24
	v_and_b32_e32 v24, 32, v41
	global_load_dwordx4 v[96:99], v24, s[0:1] offset:16
	global_load_dwordx4 v[100:103], v24, s[0:1]
	global_load_dwordx4 v[240:243], v24, s[0:1] offset:80
	global_load_dwordx4 v[244:247], v24, s[0:1] offset:64
	global_load_dwordx4 v[248:251], v24, s[0:1] offset:144
	global_load_dwordx4 v[220:223], v24, s[0:1] offset:128
	global_load_dwordx4 v[232:235], v24, s[0:1] offset:208
	global_load_dwordx4 v[236:239], v24, s[0:1] offset:192
	v_and_b32_e32 v63, 0xffff0000, v12
	v_and_b32_e32 v62, 0xffff0000, v8
	v_mov_b32_e32 v25, v177
	v_lshlrev_b32_e32 v60, 16, v9
	v_and_b32_e32 v59, 0xffff0000, v13
	v_and_b32_e32 v58, 0xffff0000, v9
	v_lshlrev_b32_e32 v65, 16, v12
	v_lshlrev_b32_e32 v64, 16, v8
	v_pk_mul_f32 v[8:9], v[62:63], v[62:63]
	v_lshl_add_u64 v[26:27], s[40:41], 0, v[24:25]
	v_lshlrev_b32_e32 v25, 7, v36
	v_lshlrev_b32_e32 v39, 16, v15
	v_and_b32_e32 v37, 0xffff0000, v15
	v_lshlrev_b32_e32 v51, 16, v14
	v_and_b32_e32 v49, 0xffff0000, v14
	v_and_b32_e32 v48, 0xffff0000, v10
	v_lshlrev_b32_e32 v61, 16, v13
	v_pk_mul_f32 v[14:15], v[58:59], v[58:59]
	v_pk_fma_f32 v[8:9], v[64:65], v[64:65], v[8:9]
	v_and_b32_e32 v28, 0x3ff80, v25
	v_mov_b32_e32 v29, v177
	v_lshlrev_b32_e32 v38, 16, v11
	v_and_b32_e32 v36, 0xffff0000, v11
	v_lshlrev_b32_e32 v50, 16, v10
	v_pk_mul_f32 v[10:11], v[48:49], v[48:49]
	v_pk_fma_f32 v[14:15], v[60:61], v[60:61], v[14:15]
	v_add_f32_e32 v8, v8, v19
	v_lshl_add_u64 v[28:29], v[26:27], 0, v[28:29]
	v_pk_mul_f32 v[26:27], v[36:37], v[36:37]
	v_pk_fma_f32 v[10:11], v[50:51], v[50:51], v[10:11]
	v_add_f32_e32 v8, v14, v8
	v_pk_fma_f32 v[26:27], v[38:39], v[38:39], v[26:27]
	v_add_f32_e32 v8, v10, v8
	v_add_f32_e32 v8, v26, v8
	v_add_f32_e32 v8, v9, v8
	v_add_f32_e32 v8, v15, v8
	v_add_f32_e32 v8, v11, v8
	v_and_b32_e32 v26, 0xffff0000, v3
	v_and_b32_e32 v32, 0xffff0000, v2
	v_add_f32_e32 v10, v27, v8
	v_lshlrev_b32_e32 v31, 16, v7
	v_lshlrev_b32_e32 v30, 16, v3
	v_and_b32_e32 v27, 0xffff0000, v7
	v_lshlrev_b32_e32 v35, 16, v6
	v_lshlrev_b32_e32 v34, 16, v2
	v_and_b32_e32 v33, 0xffff0000, v6
	v_mov_b32_e32 v6, v26
	v_mov_b32_e32 v7, v32
	v_mov_b32_e32 v2, v30
	v_mov_b32_e32 v3, v34
	v_pk_mul_f32 v[6:7], v[6:7], v[6:7]
	v_mov_b32_e32 v8, v27
	v_mov_b32_e32 v9, v33
	v_pk_fma_f32 v[2:3], v[2:3], v[2:3], v[6:7]
	v_mov_b32_e32 v6, v31
	v_mov_b32_e32 v7, v35
	v_pk_mul_f32 v[8:9], v[8:9], v[8:9]
	v_and_b32_e32 v43, 0xffff0000, v5
	v_lshlrev_b32_e32 v56, 16, v0
	v_and_b32_e32 v53, 0xffff0000, v4
	v_pk_fma_f32 v[6:7], v[6:7], v[6:7], v[8:9]
	v_lshlrev_b32_e32 v47, 16, v5
	v_lshlrev_b32_e32 v46, 16, v1
	v_lshlrev_b32_e32 v57, 16, v4
	v_and_b32_e32 v52, 0xffff0000, v0
	v_mul_f32_e32 v9, v56, v56
	v_mov_b32_e32 v4, v43
	v_mov_b32_e32 v5, v53
	v_and_b32_e32 v42, 0xffff0000, v1
	v_mul_f32_e32 v8, v46, v46
	v_fmac_f32_e32 v9, v52, v52
	v_mov_b32_e32 v0, v47
	v_mov_b32_e32 v1, v57
	v_pk_mul_f32 v[4:5], v[4:5], v[4:5]
	v_fmac_f32_e32 v8, v42, v42
	v_pk_fma_f32 v[0:1], v[0:1], v[0:1], v[4:5]
	v_add_f32_e32 v4, v9, v10
	v_add_f32_e32 v4, v8, v4
	v_add_f32_e32 v3, v3, v4
	v_add_f32_e32 v2, v2, v3
	v_add_f32_e32 v1, v1, v2
	v_add_f32_e32 v0, v0, v1
	v_add_f32_e32 v0, v7, v0
	v_add_f32_e32 v0, v6, v0
	v_mov_b32_e32 v1, v0
	s_nop 1
	v_permlane32_swap_b32_e32 v0, v1
	v_add_f32_e32 v0, v0, v1
	v_fmamk_f32 v0, v0, 0x3baaaaab, v216
	v_cmp_gt_f32_e32 vcc, s85, v0
	v_mul_f32_e32 v1, 0x4b800000, v0
	v_lshl_add_u64 v[54:55], v[28:29], 0, s[30:31]
	v_cndmask_b32_e32 v0, v0, v1, vcc
	v_rsq_f32_e32 v0, v0
	v_lshl_add_u64 v[44:45], v[28:29], 0, s[6:7]
	v_mul_f32_e32 v1, 0x45800000, v0
	v_cndmask_b32_e32 v0, v0, v1, vcc
	v_mul_f32_e32 v40, 0x3dd53b94, v0
	v_mul_f32_e32 v0, v40, v69
	v_mul_f32_e32 v1, v40, v73
	v_mul_f32_e32 v2, v40, v68
	v_mul_f32_e32 v3, v40, v72
	v_mul_f32_e32 v4, v40, v71
	v_mul_f32_e32 v5, v40, v77
	v_mul_f32_e32 v6, v40, v70
	v_mul_f32_e32 v7, v40, v76
	s_waitcnt vmcnt(0)
	v_mul_f32_e32 v0, v100, v0
	v_mul_f32_e32 v1, v96, v1
	v_mul_f32_e32 v2, v101, v2
	v_mul_f32_e32 v3, v97, v3
	v_mul_f32_e32 v4, v102, v4
	v_mul_f32_e32 v5, v98, v5
	v_mul_f32_e32 v6, v103, v6
	v_mul_f32_e32 v7, v99, v7
	v_cvt_pk_bf16_f32 v96, v0, v2
	v_cvt_pk_bf16_f32 v97, v4, v6
	v_cvt_pk_bf16_f32 v98, v1, v3
	v_cvt_pk_bf16_f32 v99, v5, v7
	s_nop 1
	v_mov_b32_e32 v0, v240
	v_mov_b32_e32 v1, v241
	v_mov_b32_e32 v2, v242
	v_mov_b32_e32 v3, v243
	v_mov_b32_e32 v4, v244
	v_mov_b32_e32 v5, v245
	v_mov_b32_e32 v6, v246
	v_mov_b32_e32 v7, v247
	global_load_dwordx4 v[240:243], v24, s[0:1] offset:272
	global_load_dwordx4 v[244:247], v24, s[0:1] offset:256
	v_mul_f32_e32 v8, v40, v75
	v_add_co_u32_e32 v76, vcc, s88, v28
	v_mul_f32_e32 v4, v4, v8
	v_mul_f32_e32 v8, v40, v82
	v_mul_f32_e32 v0, v0, v8
	v_mul_f32_e32 v8, v40, v74
	v_mul_f32_e32 v5, v5, v8
	v_mul_f32_e32 v8, v40, v80
	v_mul_f32_e32 v1, v1, v8
	v_mul_f32_e32 v8, v40, v79
	v_mul_f32_e32 v6, v6, v8
	v_mul_f32_e32 v8, v40, v86
	v_mul_f32_e32 v2, v2, v8
	v_mul_f32_e32 v8, v40, v78
	v_mul_f32_e32 v7, v7, v8
	v_mul_f32_e32 v8, v40, v85
	v_mul_f32_e32 v3, v3, v8
	v_cvt_pk_bf16_f32 v100, v4, v5
	v_cvt_pk_bf16_f32 v101, v6, v7
	v_cvt_pk_bf16_f32 v102, v0, v1
	v_cvt_pk_bf16_f32 v103, v2, v3
	s_nop 1
	v_mov_b32_e32 v0, v248
	v_mov_b32_e32 v1, v249
	v_mov_b32_e32 v2, v250
	v_mov_b32_e32 v3, v251
	v_mov_b32_e32 v4, v220
	v_mov_b32_e32 v5, v221
	v_mov_b32_e32 v6, v222
	v_mov_b32_e32 v7, v223
	global_load_dwordx4 v[248:251], v24, s[0:1] offset:336
	global_load_dwordx4 v[220:223], v24, s[0:1] offset:320
	v_mul_f32_e32 v8, v40, v84
	v_addc_co_u32_e32 v77, vcc, 0, v29, vcc
	v_mul_f32_e32 v4, v8, v4
	v_mul_f32_e32 v8, v40, v95
	v_mul_f32_e32 v0, v8, v0
	v_mul_f32_e32 v8, v40, v83
	v_mul_f32_e32 v5, v8, v5
	v_mul_f32_e32 v8, v40, v93
	v_mul_f32_e32 v1, v8, v1
	v_mul_f32_e32 v8, v40, v88
	v_mul_f32_e32 v6, v8, v6
	v_mul_f32_e32 v8, v40, v105
	v_mul_f32_e32 v2, v8, v2
	v_mul_f32_e32 v8, v40, v87
	v_mul_f32_e32 v7, v8, v7
	v_mul_f32_e32 v8, v40, v104
	v_mul_f32_e32 v3, v8, v3
	v_cvt_pk_bf16_f32 v104, v4, v5
	v_cvt_pk_bf16_f32 v105, v6, v7
	v_cvt_pk_bf16_f32 v106, v0, v1
	v_cvt_pk_bf16_f32 v107, v2, v3
	s_nop 1
	v_mov_b32_e32 v0, v232
	v_mov_b32_e32 v1, v233
	v_mov_b32_e32 v2, v234
	v_mov_b32_e32 v3, v235
	v_mov_b32_e32 v4, v236
	v_mov_b32_e32 v5, v237
	v_mov_b32_e32 v6, v238
	v_mov_b32_e32 v7, v239
	global_load_dwordx4 v[232:235], v24, s[0:1] offset:400
	global_load_dwordx4 v[236:239], v24, s[0:1] offset:384
	v_mul_f32_e32 v8, v40, v108
	v_mul_f32_e32 v4, v8, v4
	v_mul_f32_e32 v8, v40, v112
	v_mul_f32_e32 v0, v8, v0
	v_mul_f32_e32 v8, v40, v91
	v_mul_f32_e32 v5, v8, v5
	v_mul_f32_e32 v8, v40, v110
	v_mul_f32_e32 v1, v8, v1
	v_mul_f32_e32 v8, v40, v94
	v_mul_f32_e32 v6, v8, v6
	v_mul_f32_e32 v8, v40, v111
	v_mul_f32_e32 v2, v8, v2
	v_mul_f32_e32 v8, v40, v89
	v_mul_f32_e32 v7, v8, v7
	v_mul_f32_e32 v8, v40, v109
	v_mul_f32_e32 v3, v8, v3
	v_cvt_pk_bf16_f32 v108, v4, v5
	v_cvt_pk_bf16_f32 v109, v6, v7
	v_cvt_pk_bf16_f32 v110, v0, v1
	v_cvt_pk_bf16_f32 v111, v2, v3
	s_waitcnt vmcnt(4)
	s_nop 1
	v_mov_b32_e32 v0, v240
	v_mov_b32_e32 v1, v241
	v_mov_b32_e32 v2, v242
	v_mov_b32_e32 v3, v243
	v_mov_b32_e32 v4, v244
	v_mov_b32_e32 v5, v245
	v_mov_b32_e32 v6, v246
	v_mov_b32_e32 v7, v247
	global_load_dwordx4 v[240:243], v24, s[0:1] offset:464
	global_load_dwordx4 v[244:247], v24, s[0:1] offset:448
	v_mul_f32_e32 v8, v40, v113
	v_mul_f32_e32 v4, v8, v4
	v_mul_f32_e32 v8, v40, v131
	v_mul_f32_e32 v0, v8, v0
	v_mul_f32_e32 v8, v40, v114
	v_mul_f32_e32 v5, v8, v5
	v_mul_f32_e32 v8, v40, v132
	v_mul_f32_e32 v1, v8, v1
	v_mul_f32_e32 v8, v40, v115
	v_mul_f32_e32 v6, v8, v6
	v_mul_f32_e32 v8, v40, v133
	v_mul_f32_e32 v2, v8, v2
	v_mul_f32_e32 v8, v40, v130
	v_mul_f32_e32 v7, v8, v7
	v_mul_f32_e32 v8, v40, v134
	v_mul_f32_e32 v3, v8, v3
	v_cvt_pk_bf16_f32 v112, v4, v5
	v_cvt_pk_bf16_f32 v113, v6, v7
	v_cvt_pk_bf16_f32 v114, v0, v1
	v_cvt_pk_bf16_f32 v115, v2, v3
	s_waitcnt vmcnt(4)
	s_nop 1
	v_mov_b32_e32 v0, v248
	v_mov_b32_e32 v1, v249
	v_mov_b32_e32 v2, v250
	v_mov_b32_e32 v3, v251
	v_mov_b32_e32 v4, v220
	v_mov_b32_e32 v5, v221
	v_mov_b32_e32 v6, v222
	v_mov_b32_e32 v7, v223
	v_mul_f32_e32 v8, v40, v128
	v_mul_f32_e32 v4, v8, v4
	v_mul_f32_e32 v8, v40, v129
	v_mul_f32_e32 v0, v8, v0
	v_mul_f32_e32 v8, v40, v126
	v_mul_f32_e32 v5, v8, v5
	v_mul_f32_e32 v8, v40, v127
	v_mul_f32_e32 v1, v8, v1
	v_mul_f32_e32 v8, v40, v118
	v_mul_f32_e32 v6, v8, v6
	v_mul_f32_e32 v8, v40, v119
	v_mul_f32_e32 v2, v8, v2
	v_mul_f32_e32 v8, v40, v116
	v_mul_f32_e32 v7, v8, v7
	v_mul_f32_e32 v8, v40, v117
	v_mul_f32_e32 v3, v8, v3
	v_cvt_pk_bf16_f32 v116, v4, v5
	v_cvt_pk_bf16_f32 v117, v6, v7
	v_cvt_pk_bf16_f32 v118, v0, v1
	v_cvt_pk_bf16_f32 v119, v2, v3
	s_waitcnt vmcnt(2)
	s_nop 1
	v_mov_b32_e32 v0, v232
	v_mov_b32_e32 v1, v233
	v_mov_b32_e32 v2, v234
	v_mov_b32_e32 v3, v235
	v_mov_b32_e32 v4, v236
	v_mov_b32_e32 v5, v237
	v_mov_b32_e32 v6, v238
	v_mov_b32_e32 v7, v239
	v_mul_f32_e32 v8, v40, v124
	v_mul_f32_e32 v4, v8, v4
	v_mul_f32_e32 v8, v40, v125
	v_mul_f32_e32 v8, v8, v0
	v_mul_f32_e32 v0, v40, v122
	v_mul_f32_e32 v0, v0, v5
	v_mul_f32_e32 v5, v40, v123
	v_mul_f32_e32 v5, v5, v1
	v_mul_f32_e32 v1, v40, v120
	v_mul_f32_e32 v1, v1, v6
	v_mul_f32_e32 v6, v40, v121
	v_mul_f32_e32 v6, v6, v2
	v_mul_f32_e32 v2, v40, v90
	v_mul_f32_e32 v2, v2, v7
	v_mul_f32_e32 v7, v40, v92
	v_mul_f32_e32 v3, v7, v3
	v_cvt_pk_bf16_f32 v0, v4, v0
	v_cvt_pk_bf16_f32 v1, v1, v2
	v_cvt_pk_bf16_f32 v2, v8, v5
	v_cvt_pk_bf16_f32 v3, v6, v3
	ds_write_b128 v171, v[0:3]
	s_waitcnt vmcnt(0)
	s_nop 1
	v_mov_b32_e32 v0, v240
	v_mov_b32_e32 v1, v241
	v_mov_b32_e32 v2, v242
	v_mov_b32_e32 v3, v243
	v_mov_b32_e32 v4, v244
	v_mov_b32_e32 v5, v245
	v_mov_b32_e32 v6, v246
	v_mov_b32_e32 v7, v247
	v_mul_f32_e32 v8, v40, v22
	v_mul_f32_e32 v4, v8, v4
	v_mul_f32_e32 v8, v40, v81
	v_mul_f32_e32 v8, v8, v0
	v_mul_f32_e32 v0, v40, v20
	v_mul_f32_e32 v0, v0, v5
	v_mul_f32_e32 v5, v40, v18
	v_mul_f32_e32 v5, v5, v1
	v_mul_f32_e32 v1, v40, v21
	v_mul_f32_e32 v1, v1, v6
	v_mul_f32_e32 v6, v40, v23
	v_mul_f32_e32 v6, v6, v2
	v_mul_f32_e32 v2, v40, v16
	v_mul_f32_e32 v2, v2, v7
	v_mul_f32_e32 v7, v40, v17
	v_mul_f32_e32 v3, v7, v3
	v_cvt_pk_bf16_f32 v0, v4, v0
	v_cvt_pk_bf16_f32 v1, v1, v2
	v_cvt_pk_bf16_f32 v2, v8, v5
	v_cvt_pk_bf16_f32 v3, v6, v3
	ds_write_b128 v171, v[0:3] offset:1024
	global_load_dwordx4 v[4:7], v24, s[0:1] offset:528
	global_load_dwordx4 v[16:19], v24, s[0:1] offset:512
	global_load_dwordx4 v[8:11], v24, s[0:1] offset:592
	global_load_dwordx4 v[20:23], v24, s[0:1] offset:576
	global_load_dwordx4 v[0:3], v[28:29], off offset:16
	global_load_dwordx4 v[12:15], v[28:29], off
	global_load_dwordx4 v[68:71], v[76:77], off
	global_load_dwordx4 v[72:75], v[54:55], off offset:16
	v_pk_mul_f32 v[54:55], v[40:41], v[64:65] op_sel_hi:[0,1]
	s_waitcnt vmcnt(6)
	v_mov_b32_e32 v64, v16
	s_waitcnt vmcnt(4)
	v_mov_b32_e32 v65, v20
	v_pk_mul_f32 v[54:55], v[54:55], v[64:65]
	s_waitcnt vmcnt(2)
	v_mov_b32_e32 v64, v12
	s_waitcnt vmcnt(1)
	v_mov_b32_e32 v65, v68
	v_pk_mul_f32 v[64:65], v[54:55], v[64:65]
	v_mov_b32_e32 v20, v17
	v_sub_f32_e32 v16, v64, v65
	v_mov_b32_e32 v64, v68
	v_mov_b32_e32 v65, v12
	v_pk_mul_f32 v[64:65], v[54:55], v[64:65]
	v_cndmask_b32_e64 v25, v54, v16, s[2:3]
	v_add_f32_e32 v12, v65, v64
	v_cndmask_b32_e64 v64, v55, v12, s[2:3]
	v_pk_mul_f32 v[54:55], v[40:41], v[62:63] op_sel_hi:[0,1]
	v_pk_mul_f32 v[16:17], v[54:55], v[20:21]
	v_mov_b32_e32 v68, v13
	v_pk_mul_f32 v[20:21], v[16:17], v[68:69]
	v_or_b32_e32 v65, 32, v176
	v_sub_f32_e32 v12, v20, v21
	v_cndmask_b32_e64 v20, v16, v12, s[2:3]
	v_mov_b32_e32 v12, v69
	v_pk_mul_f32 v[12:13], v[16:17], v[12:13]
	v_mov_b32_e32 v16, v18
	v_add_f32_e32 v12, v13, v12
	v_cndmask_b32_e64 v21, v17, v12, s[2:3]
	v_pk_mul_f32 v[12:13], v[40:41], v[60:61] op_sel_hi:[0,1]
	v_mov_b32_e32 v17, v22
	v_pk_mul_f32 v[12:13], v[12:13], v[16:17]
	v_mov_b32_e32 v16, v14
	v_mov_b32_e32 v17, v70
	v_pk_mul_f32 v[16:17], v[12:13], v[16:17]
	v_mov_b32_e32 v22, v19
	v_sub_f32_e32 v16, v16, v17
	v_cndmask_b32_e64 v18, v12, v16, s[2:3]
	v_mov_b32_e32 v16, v70
	v_mov_b32_e32 v17, v14
	v_pk_mul_f32 v[16:17], v[12:13], v[16:17]
	v_mov_b32_e32 v70, v15
	v_add_f32_e32 v12, v17, v16
	v_cndmask_b32_e64 v54, v13, v12, s[2:3]
	v_pk_mul_f32 v[12:13], v[40:41], v[58:59] op_sel_hi:[0,1]
	v_pk_mul_f32 v[12:13], v[12:13], v[22:23]
	v_mul_u32_u24_e32 v59, 0x180, v168
	v_pk_mul_f32 v[16:17], v[12:13], v[70:71]
	s_nop 0
	v_sub_f32_e32 v14, v16, v17
	v_cndmask_b32_e64 v16, v12, v14, s[2:3]
	v_mov_b32_e32 v14, v71
	v_pk_mul_f32 v[14:15], v[12:13], v[14:15]
	s_nop 0
	v_add_f32_e32 v12, v15, v14
	v_cndmask_b32_e64 v17, v13, v12, s[2:3]
	v_pk_mul_f32 v[12:13], v[40:41], v[50:51] op_sel_hi:[0,1]
	v_mov_b32_e32 v14, v4
	v_mov_b32_e32 v15, v8
	v_pk_mul_f32 v[12:13], v[12:13], v[14:15]
	v_mov_b32_e32 v14, v0
	s_waitcnt vmcnt(0)
	v_mov_b32_e32 v15, v72
	v_pk_mul_f32 v[14:15], v[12:13], v[14:15]
	v_mov_b32_e32 v8, v5
	v_sub_f32_e32 v4, v14, v15
	v_mov_b32_e32 v14, v72
	v_mov_b32_e32 v15, v0
	v_pk_mul_f32 v[14:15], v[12:13], v[14:15]
	v_cndmask_b32_e64 v19, v12, v4, s[2:3]
	v_add_f32_e32 v0, v15, v14
	v_cndmask_b32_e64 v14, v13, v0, s[2:3]
	v_pk_mul_f32 v[12:13], v[40:41], v[48:49] op_sel_hi:[0,1]
	v_pk_mul_f32 v[4:5], v[12:13], v[8:9]
	v_mov_b32_e32 v72, v1
	v_pk_mul_f32 v[8:9], v[4:5], v[72:73]
	s_nop 0
	v_sub_f32_e32 v0, v8, v9
	v_cndmask_b32_e64 v8, v4, v0, s[2:3]
	v_mov_b32_e32 v0, v73
	v_pk_mul_f32 v[0:1], v[4:5], v[0:1]
	v_mov_b32_e32 v4, v6
	v_add_f32_e32 v0, v1, v0
	v_cndmask_b32_e64 v9, v5, v0, s[2:3]
	v_pk_mul_f32 v[0:1], v[40:41], v[38:39] op_sel_hi:[0,1]
	v_mov_b32_e32 v5, v10
	v_pk_mul_f32 v[0:1], v[0:1], v[4:5]
	v_mov_b32_e32 v4, v2
	v_mov_b32_e32 v5, v74
	v_pk_mul_f32 v[4:5], v[0:1], v[4:5]
	v_mov_b32_e32 v10, v7
	v_sub_f32_e32 v4, v4, v5
	v_cndmask_b32_e64 v6, v0, v4, s[2:3]
	v_mov_b32_e32 v4, v74
	v_mov_b32_e32 v5, v2
	v_pk_mul_f32 v[4:5], v[0:1], v[4:5]
	v_mov_b32_e32 v74, v3
	v_add_f32_e32 v0, v5, v4
	v_cndmask_b32_e64 v12, v1, v0, s[2:3]
	v_pk_mul_f32 v[0:1], v[40:41], v[36:37] op_sel_hi:[0,1]
	v_pk_mul_f32 v[0:1], v[0:1], v[10:11]
	s_nop 0
	v_pk_mul_f32 v[4:5], v[0:1], v[74:75]
	s_nop 0
	v_sub_f32_e32 v2, v4, v5
	v_cndmask_b32_e64 v4, v0, v2, s[2:3]
	v_mov_b32_e32 v2, v75
	v_pk_mul_f32 v[2:3], v[0:1], v[2:3]
	s_nop 0
	v_add_f32_e32 v0, v3, v2
	v_cndmask_b32_e64 v5, v1, v0, s[2:3]
	v_cvt_pk_bf16_f32 v0, v25, v20
	v_cvt_pk_bf16_f32 v1, v18, v16
	v_cvt_pk_bf16_f32 v2, v19, v8
	v_cvt_pk_bf16_f32 v3, v6, v4
	ds_write_b128 v171, v[0:3] offset:2048
	v_cvt_pk_bf16_f32 v0, v64, v21
	v_cvt_pk_bf16_f32 v1, v54, v17
	v_cvt_pk_bf16_f32 v2, v14, v9
	v_cvt_pk_bf16_f32 v3, v12, v5
	ds_write_b128 v171, v[0:3] offset:3072
	global_load_dwordx4 v[0:3], v24, s[0:1] offset:656
	global_load_dwordx4 v[4:7], v24, s[0:1] offset:640
	global_load_dwordx4 v[8:11], v24, s[0:1] offset:720
	global_load_dwordx4 v[12:15], v24, s[0:1] offset:704
	global_load_dwordx4 v[16:19], v[28:29], off offset:80
	global_load_dwordx4 v[20:23], v[28:29], off offset:64
	global_load_dwordx4 v[36:39], v[76:77], off offset:64
	global_load_dwordx4 v[48:51], v[44:45], off offset:16
	v_pk_mul_f32 v[24:25], v[40:41], v[56:57] op_sel_hi:[0,1]
	s_waitcnt vmcnt(6)
	v_mov_b32_e32 v28, v4
	s_waitcnt vmcnt(4)
	v_mov_b32_e32 v29, v12
	v_pk_mul_f32 v[24:25], v[24:25], v[28:29]
	s_waitcnt vmcnt(2)
	v_mov_b32_e32 v28, v20
	s_waitcnt vmcnt(1)
	v_mov_b32_e32 v29, v36
	v_pk_mul_f32 v[28:29], v[24:25], v[28:29]
	v_mov_b32_e32 v12, v5
	v_sub_f32_e32 v4, v28, v29
	v_mov_b32_e32 v28, v36
	v_mov_b32_e32 v29, v20
	v_pk_mul_f32 v[28:29], v[24:25], v[28:29]
	v_cndmask_b32_e64 v44, v24, v4, s[2:3]
	v_add_f32_e32 v4, v29, v28
	v_cndmask_b32_e64 v28, v25, v4, s[2:3]
	v_pk_mul_f32 v[24:25], v[40:41], v[52:53] op_sel_hi:[0,1]
	v_pk_mul_f32 v[4:5], v[24:25], v[12:13]
	v_mov_b32_e32 v36, v21
	v_pk_mul_f32 v[12:13], v[4:5], v[36:37]
	v_mov_b32_e32 v20, v37
	v_sub_f32_e32 v12, v12, v13
	v_cndmask_b32_e64 v24, v4, v12, s[2:3]
	v_pk_mul_f32 v[12:13], v[4:5], v[20:21]
	s_nop 0
	v_add_f32_e32 v4, v13, v12
	v_cndmask_b32_e64 v20, v5, v4, s[2:3]
	v_pk_mul_f32 v[4:5], v[40:41], v[46:47] op_sel_hi:[0,1]
	v_mov_b32_e32 v12, v6
	v_mov_b32_e32 v13, v14
	v_pk_mul_f32 v[4:5], v[4:5], v[12:13]
	v_mov_b32_e32 v12, v22
	v_mov_b32_e32 v13, v38
	v_pk_mul_f32 v[12:13], v[4:5], v[12:13]
	v_mov_b32_e32 v14, v7
	v_sub_f32_e32 v6, v12, v13
	v_mov_b32_e32 v12, v38
	v_mov_b32_e32 v13, v22
	v_pk_mul_f32 v[12:13], v[4:5], v[12:13]
	v_cndmask_b32_e64 v21, v4, v6, s[2:3]
	v_add_f32_e32 v4, v13, v12
	v_cndmask_b32_e64 v12, v5, v4, s[2:3]
	v_pk_mul_f32 v[4:5], v[40:41], v[42:43] op_sel_hi:[0,1]
	v_pk_mul_f32 v[4:5], v[4:5], v[14:15]
	v_mov_b32_e32 v38, v23
	v_pk_mul_f32 v[6:7], v[4:5], v[38:39]
	v_mov_b32_e32 v22, v39
	v_sub_f32_e32 v6, v6, v7
	v_cndmask_b32_e64 v13, v4, v6, s[2:3]
	v_pk_mul_f32 v[6:7], v[4:5], v[22:23]
	s_nop 0
	v_add_f32_e32 v4, v7, v6
	v_cndmask_b32_e64 v14, v5, v4, s[2:3]
	v_pk_mul_f32 v[4:5], v[40:41], v[34:35] op_sel_hi:[0,1]
	v_mov_b32_e32 v6, v0
	v_mov_b32_e32 v7, v8
	v_pk_mul_f32 v[4:5], v[4:5], v[6:7]
	v_mov_b32_e32 v6, v16
	s_waitcnt vmcnt(0)
	v_mov_b32_e32 v7, v48
	v_pk_mul_f32 v[6:7], v[4:5], v[6:7]
	v_mov_b32_e32 v8, v1
	v_sub_f32_e32 v0, v6, v7
	v_mov_b32_e32 v6, v48
	v_mov_b32_e32 v7, v16
	v_pk_mul_f32 v[6:7], v[4:5], v[6:7]
	v_cndmask_b32_e64 v15, v4, v0, s[2:3]
	v_add_f32_e32 v0, v7, v6
	v_cndmask_b32_e64 v6, v5, v0, s[2:3]
	v_pk_mul_f32 v[4:5], v[40:41], v[32:33] op_sel_hi:[0,1]
	v_pk_mul_f32 v[0:1], v[4:5], v[8:9]
	v_mov_b32_e32 v48, v17
	v_pk_mul_f32 v[4:5], v[0:1], v[48:49]
	v_mov_b32_e32 v16, v49
	v_sub_f32_e32 v4, v4, v5
	v_cndmask_b32_e64 v7, v0, v4, s[2:3]
	v_pk_mul_f32 v[4:5], v[0:1], v[16:17]
	v_mov_b32_e32 v49, v177
	v_add_f32_e32 v0, v5, v4
	v_cndmask_b32_e64 v8, v1, v0, s[2:3]
	v_pk_mul_f32 v[0:1], v[40:41], v[30:31] op_sel_hi:[0,1]
	v_mov_b32_e32 v4, v2
	v_mov_b32_e32 v5, v10
	v_pk_mul_f32 v[0:1], v[0:1], v[4:5]
	v_mov_b32_e32 v4, v18
	v_mov_b32_e32 v5, v50
	v_pk_mul_f32 v[4:5], v[0:1], v[4:5]
	v_mov_b32_e32 v10, v3
	v_sub_f32_e32 v2, v4, v5
	v_mov_b32_e32 v4, v50
	v_mov_b32_e32 v5, v18
	v_pk_mul_f32 v[4:5], v[0:1], v[4:5]
	v_cndmask_b32_e64 v9, v0, v2, s[2:3]
	v_add_f32_e32 v0, v5, v4
	v_cndmask_b32_e64 v4, v1, v0, s[2:3]
	v_pk_mul_f32 v[0:1], v[40:41], v[26:27] op_sel_hi:[0,1]
	v_pk_mul_f32 v[0:1], v[0:1], v[10:11]
	v_mov_b32_e32 v50, v19
	v_pk_mul_f32 v[2:3], v[0:1], v[50:51]
	v_mov_b32_e32 v18, v51
	v_sub_f32_e32 v2, v2, v3
	v_cndmask_b32_e64 v5, v0, v2, s[2:3]
	v_pk_mul_f32 v[2:3], v[0:1], v[18:19]
	v_lshlrev_b32_e32 v18, 4, v41
	v_add_f32_e32 v0, v3, v2
	v_cndmask_b32_e64 v10, v1, v0, s[2:3]
	v_cvt_pk_bf16_f32 v0, v44, v24
	v_cvt_pk_bf16_f32 v1, v21, v13
	v_cvt_pk_bf16_f32 v2, v15, v7
	v_cvt_pk_bf16_f32 v3, v9, v5
	ds_write_b128 v171, v[0:3] offset:4096
	v_cvt_pk_bf16_f32 v0, v28, v20
	v_cvt_pk_bf16_f32 v1, v12, v14
	v_cvt_pk_bf16_f32 v2, v6, v8
	v_cvt_pk_bf16_f32 v3, v4, v10
	ds_write_b128 v171, v[0:3] offset:5120
	v_and_b32_e32 v1, 0xfffff0, v148
	v_lshlrev_b32_e32 v3, 1, v148
	v_lshlrev_b32_e32 v0, 3, v41
	v_and_or_b32 v1, v3, 8, v1
	v_and_b32_e32 v2, 0x78, v0
	v_lshrrev_b32_e32 v3, 1, v148
	v_lshrrev_b32_e32 v1, 1, v1
	v_bfe_u32 v0, v0, 5, 2
	v_and_b32_e32 v4, 3, v148
	v_or_b32_e32 v1, v1, v0
	v_and_or_b32 v3, v3, 4, v4
	v_lshlrev_b32_e32 v1, 9, v1
	v_lshlrev_b32_e32 v3, 6, v3
	v_and_b32_e32 v4, 48, v18
	v_or3_b32 v19, v1, v3, v4
	v_add_u32_e32 v1, 32, v148
	v_and_b32_e32 v5, 0xfffff0, v1
	v_lshlrev_b32_e32 v1, 1, v1
	v_and_or_b32 v1, v1, 8, v5
	v_lshrrev_b32_e32 v1, 1, v1
	v_or_b32_e32 v0, v1, v0
	v_lshlrev_b32_e32 v0, 9, v0
	s_mov_b32 s2, 0x2aaaaaab
	v_or3_b32 v20, v0, v3, v4
	v_mul_hi_i32 v0, v41, s2
	v_lshrrev_b32_e32 v1, 31, v0
	v_ashrrev_i32_e32 v0, 2, v0
	v_add_u32_e32 v150, v0, v1
	v_add_u32_e32 v1, 0x200, v41
	v_mul_hi_i32 v3, v1, s2
	v_lshrrev_b32_e32 v4, 31, v3
	v_ashrrev_i32_e32 v3, 2, v3
	v_add_u32_e32 v152, v3, v4
	v_mul_lo_u32 v3, v152, 24
	v_sub_u32_e32 v1, v1, v3
	v_add_u32_e32 v3, 0x400, v41
	v_mul_hi_i32 v4, v3, s2
	v_lshrrev_b32_e32 v5, 31, v4
	v_ashrrev_i32_e32 v4, 2, v4
	v_mul_lo_u32 v0, v150, 24
	v_add_u32_e32 v154, v4, v5
	s_add_u32 s2, s94, s44
	v_sub_u32_e32 v0, v41, v0
	v_mul_lo_u32 v4, v154, 24
	s_addc_u32 s3, s95, 0
	s_lshl_b32 s5, s5, 8
	v_lshlrev_b32_e32 v8, 3, v0
	v_sub_u32_e32 v3, v3, v4
	v_mul_lo_u32 v4, v150, s89
	v_bitop3_b32 v0, v150, v0, 7 bitop3:0x6c
	s_add_u32 s6, s38, s5
	v_lshlrev_b32_e32 v12, 3, v1
	v_lshl_add_u32 v21, v0, 4, v4
	v_mul_lo_u32 v0, v152, s89
	v_bitop3_b32 v1, v152, v1, 7 bitop3:0x6c
	s_addc_u32 s7, s39, 0
	s_ashr_i32 s5, s4, 31
	v_ashrrev_i32_e32 v151, 31, v150
	v_lshl_add_u32 v22, v1, 4, v0
	v_mul_lo_u32 v0, v154, s89
	v_bitop3_b32 v1, v154, v3, 7 bitop3:0x6c
	v_lshl_add_u64 v[10:11], v[150:151], 0, s[4:5]
	v_mov_b64_e32 v[52:53], s[2:3]
	v_lshlrev_b32_e32 v16, 3, v3
	v_lshl_add_u32 v23, v1, 4, v0
	v_lshlrev_b32_e32 v0, 3, v66
	v_and_b32_e32 v1, 0xc0, v67
	v_lshlrev_b32_e32 v3, 1, v41
	v_ashrrev_i32_e32 v9, 31, v8
	v_mad_u64_u32 v[14:15], s[18:19], v10, s87, v[52:53]
	v_and_or_b32 v1, v0, 24, v1
	v_and_b32_e32 v3, 32, v3
	v_and_b32_e32 v0, 0x100, v0
	v_mad_i32_i24 v15, v11, s87, v15
	v_lshlrev_b64 v[50:51], 1, v[8:9]
	v_ashrrev_i32_e32 v153, 31, v152
	v_or3_b32 v58, v1, v3, v0
	v_lshl_add_u64 v[0:1], v[148:149], 0, s[4:5]
	v_lshl_add_u64 v[8:9], v[14:15], 0, v[50:51]
	v_lshl_add_u64 v[14:15], v[152:153], 0, s[4:5]
	v_lshlrev_b64 v[0:1], 11, v[0:1]
	v_ashrrev_i32_e32 v13, 31, v12
	v_mad_u64_u32 v[24:25], s[18:19], v14, s87, v[52:53]
	v_lshl_add_u64 v[0:1], s[6:7], 0, v[0:1]
	v_lshlrev_b32_e32 v48, 1, v2
	v_mad_i32_i24 v25, v15, s87, v25
	v_lshlrev_b64 v[54:55], 1, v[12:13]
	v_ashrrev_i32_e32 v155, 31, v154
	v_lshl_add_u64 v[0:1], v[0:1], 0, v[48:49]
	v_lshl_add_u64 v[4:5], v[156:157], 0, s[4:5]
	v_lshl_add_u64 v[12:13], v[24:25], 0, v[54:55]
	v_lshl_add_u64 v[24:25], v[154:155], 0, s[4:5]
	global_load_dwordx4 v[0:3], v[0:1], off
	v_lshlrev_b64 v[4:5], 11, v[4:5]
	v_ashrrev_i32_e32 v17, 31, v16
	v_mad_u64_u32 v[26:27], s[18:19], v24, s87, v[52:53]
	v_lshl_add_u64 v[4:5], s[6:7], 0, v[4:5]
	v_mad_i32_i24 v27, v25, s87, v27
	v_lshlrev_b64 v[56:57], 1, v[16:17]
	v_lshl_add_u64 v[4:5], v[4:5], 0, v[48:49]
	v_lshl_add_u64 v[16:17], v[26:27], 0, v[56:57]
	global_load_dwordx4 v[4:7], v[4:5], off
	v_add_u32_e32 v182, 0, v19
	global_load_dwordx4 v[8:11], v[8:9], off
	v_and_b32_e32 v72, 0x70, v18
	global_load_dwordx4 v[12:15], v[12:13], off
	v_add_u32_e32 v183, 0, v20
	global_load_dwordx4 v[24:27], v[16:17], off
	s_waitcnt vmcnt(0)
	v_add_u32_e32 v184, 0, v21
	v_add_u32_e32 v185, 0, v22
	v_add_u32_e32 v186, 0, v23
	v_bitop3_b32 v60, v65, v59, v72 bitop3:0xde
	v_add_u32_e32 v189, 0, v60
	s_movk_i32 s5, 0x80
	s_mov_b32 s44, s45
	v_add_u32_e32 v172, s16, v58
	v_lshl_add_u64 v[160:161], s[6:7], 0, v[48:49]
	v_lshl_add_u64 v[162:163], s[2:3], 0, v[50:51]
	v_lshl_add_u64 v[164:165], s[2:3], 0, v[54:55]
	v_lshl_add_u64 v[166:167], s[2:3], 0, v[56:57]
	v_cmp_gt_u32_e64 s[2:3], 32, v66
	s_waitcnt vmcnt(4)
	ds_write_b128 v182, v[0:3]
	v_mov_b32_e32 v0, 0x3000
	v_mad_u32_u24 v71, v168, s89, v0
	v_bitop3_b32 v0, v176, v59, v72 bitop3:0xde
	v_add_u32_e32 v187, 0, v0
	v_bitop3_b32 v67, v65, v71, v72 bitop3:0xde
	v_bitop3_b32 v64, v176, v71, v72 bitop3:0xde
	v_add_u32_e32 v202, 0, v64
	v_add_u32_e32 v201, 0, v67
	s_waitcnt vmcnt(3)
	ds_write_b128 v183, v[4:7]
	s_waitcnt vmcnt(2)
	ds_write_b128 v184, v[8:11] offset:32768
	s_waitcnt vmcnt(1)
	ds_write_b128 v185, v[12:15] offset:32768
	v_mov_b64_e32 v[0:1], s[44:45]
	s_waitcnt vmcnt(0)
	ds_write_b128 v186, v[24:27] offset:32768
	s_waitcnt lgkmcnt(0)
	s_barrier
	ds_read_b128 v[16:19], v187 offset:32768
	ds_read_b128 v[20:23], v187 offset:45056
	ds_read_b128 v[60:63], v189 offset:32768
	ds_read_b128 v[74:77], v189 offset:45056
	s_waitcnt lgkmcnt(3)
	v_mfma_f32_32x32x16_bf16 v[32:47], v[16:19], v[96:99], 0
	v_mov_b64_e32 v[14:15], s[58:59]
	v_mov_b64_e32 v[2:3], s[46:47]
	v_mov_b64_e32 v[4:5], s[48:49]
	v_mov_b64_e32 v[6:7], s[50:51]
	v_mov_b64_e32 v[8:9], s[52:53]
	v_mov_b64_e32 v[10:11], s[54:55]
	v_mov_b64_e32 v[12:13], s[56:57]
	s_waitcnt lgkmcnt(2)
	v_mfma_f32_32x32x16_bf16 v[16:31], v[20:23], v[96:99], 0
	s_waitcnt lgkmcnt(1)
	v_mfma_f32_32x32x16_bf16 v[32:47], v[60:63], v[100:103], v[32:47]
	v_or_b32_e32 v60, 64, v176
	v_bitop3_b32 v61, v60, v59, v72 bitop3:0xde
	v_add_u32_e32 v190, 0, v61
	ds_read_b128 v[78:81], v190 offset:45056
	v_bitop3_b32 v61, v60, v71, v72 bitop3:0xde
	v_or_b32_e32 v60, 0x60, v176
	v_bitop3_b32 v59, v60, v59, v72 bitop3:0xde
	s_waitcnt lgkmcnt(1)
	v_mfma_f32_32x32x16_bf16 v[16:31], v[74:77], v[100:103], v[16:31]
	ds_read_b128 v[74:77], v190 offset:32768
	v_add_u32_e32 v191, 0, v59
	v_bitop3_b32 v59, v60, v71, v72 bitop3:0xde
	v_bitop3_b32 v60, v176, v72, s5 bitop3:0x36
	v_mad_u32_u24 v62, v168, s89, v60
	v_add_u32_e32 v192, 0, v62
	s_movk_i32 s5, 0xa0
	s_waitcnt lgkmcnt(0)
	v_mfma_f32_32x32x16_bf16 v[32:47], v[74:77], v[104:107], v[32:47]
	ds_read_b128 v[74:77], v191 offset:32768
	v_bitop3_b32 v62, v176, v72, s5 bitop3:0x36
	v_mad_u32_u24 v63, v168, s89, v62
	v_add_u32_e32 v193, 0, v63
	s_movk_i32 s5, 0xc0
	v_bitop3_b32 v63, v176, v72, s5 bitop3:0x36
	v_mad_u32_u24 v65, v168, s89, v63
	v_mfma_f32_32x32x16_bf16 v[16:31], v[78:81], v[104:107], v[16:31]
	ds_read_b128 v[78:81], v191 offset:45056
	v_add_u32_e32 v194, 0, v65
	s_movk_i32 s5, 0xe0
	v_bitop3_b32 v65, v176, v72, s5 bitop3:0x36
	v_mad_u32_u24 v68, v168, s89, v65
	v_add_u32_e32 v195, 0, v68
	s_movk_i32 s5, 0x100
	s_waitcnt lgkmcnt(1)
	v_mfma_f32_32x32x16_bf16 v[32:47], v[74:77], v[108:111], v[32:47]
	ds_read_b128 v[74:77], v192 offset:32768
	v_bitop3_b32 v68, v176, v72, s5 bitop3:0x36
	v_mad_u32_u24 v69, v168, s89, v68
	v_add_u32_e32 v196, 0, v69
	s_movk_i32 s5, 0x120
	v_bitop3_b32 v69, v176, v72, s5 bitop3:0x36
	v_mad_u32_u24 v70, v168, s89, v69
	s_waitcnt lgkmcnt(1)
	v_mfma_f32_32x32x16_bf16 v[16:31], v[78:81], v[108:111], v[16:31]
	ds_read_b128 v[78:81], v192 offset:45056
	v_add_u32_e32 v197, 0, v70
	s_movk_i32 s5, 0x140
	v_bitop3_b32 v70, v176, v72, s5 bitop3:0x36
	v_mad_u32_u24 v73, v168, s89, v70
	v_add_u32_e32 v199, 0, v73
	s_movk_i32 s5, 0x160
	s_waitcnt lgkmcnt(1)
	v_mfma_f32_32x32x16_bf16 v[32:47], v[74:77], v[112:115], v[32:47]
	ds_read_b128 v[74:77], v193 offset:32768
	v_add_u32_e32 v60, v60, v71
	v_add_u32_e32 v62, v62, v71
	v_add_u32_e32 v63, v63, v71
	v_add_u32_e32 v65, v65, v71
	v_add_u32_e32 v68, v68, v71
	v_add_u32_e32 v69, v69, v71
	s_waitcnt lgkmcnt(1)
	v_mfma_f32_32x32x16_bf16 v[16:31], v[78:81], v[112:115], v[16:31]
	ds_read_b128 v[78:81], v193 offset:45056
	v_add_u32_e32 v70, v70, v71
	v_add_u32_e32 v209, 0, v61
	v_add_u32_e32 v212, 0, v59
	v_add_u32_e32 v211, 0, v60
	v_add_u32_e32 v210, 0, v62
	v_add_u32_e32 v208, 0, v63
	s_waitcnt lgkmcnt(1)
	v_mfma_f32_32x32x16_bf16 v[32:47], v[74:77], v[116:119], v[32:47]
	ds_read_b128 v[74:77], v194 offset:32768
	v_add_u32_e32 v207, 0, v65
	v_add_u32_e32 v206, 0, v68
	v_add_u32_e32 v205, 0, v69
	v_add_u32_e32 v204, 0, v70
	s_waitcnt lgkmcnt(1)
	v_mfma_f32_32x32x16_bf16 v[16:31], v[78:81], v[116:119], v[16:31]
	ds_read_b128 v[78:81], v194 offset:45056
	ds_read_b128 v[82:85], v171
	s_waitcnt lgkmcnt(0)
	v_mfma_f32_32x32x16_bf16 v[32:47], v[74:77], v[82:85], v[32:47]
	ds_read_b128 v[74:77], v195 offset:32768
	v_mfma_f32_32x32x16_bf16 v[16:31], v[78:81], v[82:85], v[16:31]
	ds_read_b128 v[78:81], v195 offset:45056
	ds_read_b128 v[82:85], v171 offset:1024
	s_waitcnt lgkmcnt(0)
	v_mfma_f32_32x32x16_bf16 v[32:47], v[74:77], v[82:85], v[32:47]
	ds_read_b128 v[74:77], v196 offset:32768
	v_mfma_f32_32x32x16_bf16 v[16:31], v[78:81], v[82:85], v[16:31]
	ds_read_b128 v[78:81], v196 offset:45056
	ds_read_b128 v[82:85], v171 offset:2048
	s_waitcnt lgkmcnt(0)
	v_mfma_f32_32x32x16_bf16 v[32:47], v[74:77], v[82:85], v[32:47]
	ds_read_b128 v[74:77], v197 offset:32768
	v_mfma_f32_32x32x16_bf16 v[16:31], v[78:81], v[82:85], v[16:31]
	ds_read_b128 v[78:81], v197 offset:45056
	ds_read_b128 v[82:85], v171 offset:3072
	s_waitcnt lgkmcnt(0)
	v_mfma_f32_32x32x16_bf16 v[32:47], v[74:77], v[82:85], v[32:47]
	ds_read_b128 v[74:77], v199 offset:32768
	v_mfma_f32_32x32x16_bf16 v[16:31], v[78:81], v[82:85], v[16:31]
	ds_read_b128 v[78:81], v199 offset:45056
	ds_read_b128 v[82:85], v171 offset:4096
	s_waitcnt lgkmcnt(0)
	v_mfma_f32_32x32x16_bf16 v[32:47], v[74:77], v[82:85], v[32:47]
	v_bitop3_b32 v76, v176, v72, s5 bitop3:0x36
	v_mad_u32_u24 v72, v168, s89, v76
	v_add_u32_e32 v198, 0, v72
	ds_read_b128 v[72:75], v198 offset:32768
	v_add_u32_e32 v71, v76, v71
	v_add_u32_e32 v203, 0, v71
	v_mfma_f32_32x32x16_bf16 v[16:31], v[78:81], v[82:85], v[16:31]
	ds_read_b128 v[76:79], v198 offset:45056
	ds_read_b128 v[80:83], v171 offset:5120
	s_waitcnt lgkmcnt(0)
	v_mfma_f32_32x32x16_bf16 v[32:47], v[72:75], v[80:83], v[32:47]
	v_mov_b32_e32 v74, 0xf149f2ca
	v_mfma_f32_32x32x16_bf16 v[16:31], v[76:79], v[80:83], v[16:31]
	s_nop 9
	v_max_f32_e32 v72, v33, v33
	v_max_f32_e32 v73, v32, v32
	v_max_f32_e32 v72, v73, v72
	v_max3_f32 v72, v72, v34, v35
	v_max3_f32 v72, v72, v36, v37
	v_max3_f32 v72, v72, v38, v39
	v_max3_f32 v72, v72, v40, v41
	v_max3_f32 v72, v72, v42, v43
	v_max3_f32 v72, v72, v44, v45
	v_max3_f32 v72, v72, v46, v47
	v_max3_f32 v72, v72, v16, v17
	v_max3_f32 v72, v72, v18, v19
	v_max3_f32 v72, v72, v20, v21
	v_max3_f32 v72, v72, v22, v23
	v_max3_f32 v72, v72, v24, v25
	v_max3_f32 v72, v72, v26, v27
	v_max3_f32 v72, v72, v28, v29
	v_max3_f32 v72, v72, v30, v31
	v_mov_b32_e32 v73, v72
	s_nop 1
	v_permlane32_swap_b32_e32 v72, v73
	v_max_f32_e32 v73, v73, v73
	v_max_f32_e32 v72, v72, v72
	v_max_f32_e32 v72, v72, v73
	v_add_f32_e32 v73, 0x7149f2ca, v72
	v_cmp_ge_f32_e32 vcc, s90, v73
	s_cmp_eq_u64 vcc, exec
	s_cselect_b64 vcc, -1, 0
	v_max_f32_e32 v72, 0xf149f2ca, v72
	s_add_i32 s18, s15, 0x8040
	v_cndmask_b32_e32 v158, v72, v74, vcc
	s_ashr_i32 s19, s18, 31
	v_sub_f32_e32 v132, v16, v158
	v_sub_f32_e32 v133, v17, v158
	v_lshl_add_u64 v[16:17], v[148:149], 0, s[18:19]
	v_sub_f32_e32 v124, v20, v158
	v_sub_f32_e32 v125, v21, v158
	v_lshlrev_b64 v[16:17], 11, v[16:17]
	v_lshl_add_u64 v[20:21], v[156:157], 0, s[18:19]
	v_sub_f32_e32 v128, v24, v158
	v_sub_f32_e32 v129, v25, v158
	v_lshl_add_u64 v[16:17], s[6:7], 0, v[16:17]
	v_lshlrev_b64 v[20:21], 11, v[20:21]
	v_lshl_add_u64 v[24:25], v[150:151], 0, s[18:19]
	v_sub_f32_e32 v32, v32, v158
	v_sub_f32_e32 v33, v33, v158
	v_sub_f32_e32 v130, v26, v158
	v_sub_f32_e32 v131, v27, v158
	v_sub_f32_e32 v120, v28, v158
	v_sub_f32_e32 v121, v29, v158
	v_lshl_add_u64 v[16:17], v[16:17], 0, v[48:49]
	v_lshl_add_u64 v[20:21], s[6:7], 0, v[20:21]
	v_mad_u64_u32 v[26:27], s[20:21], v24, s87, v[52:53]
	v_lshl_add_u64 v[28:29], v[152:153], 0, s[18:19]
	v_sub_f32_e32 v34, v34, v158
	v_sub_f32_e32 v35, v35, v158
	v_sub_f32_e32 v134, v18, v158
	v_sub_f32_e32 v135, v19, v158
	v_sub_f32_e32 v122, v30, v158
	v_sub_f32_e32 v123, v31, v158
	v_exp_f32_e32 v136, v32
	v_exp_f32_e32 v230, v33
	global_load_dwordx4 v[16:19], v[16:17], off
	v_lshl_add_u64 v[20:21], v[20:21], 0, v[48:49]
	v_mad_i32_i24 v27, v25, s87, v27
	v_mad_u64_u32 v[30:31], s[20:21], v28, s87, v[52:53]
	v_lshl_add_u64 v[32:33], v[154:155], 0, s[18:19]
	v_sub_f32_e32 v126, v22, v158
	v_sub_f32_e32 v127, v23, v158
	v_exp_f32_e32 v137, v34
	v_exp_f32_e32 v229, v35
	global_load_dwordx4 v[20:23], v[20:21], off
	v_lshl_add_u64 v[24:25], v[26:27], 0, v[50:51]
	v_mad_i32_i24 v31, v29, s87, v31
	v_mad_u64_u32 v[34:35], s[18:19], v32, s87, v[52:53]
	global_load_dwordx4 v[24:27], v[24:25], off
	v_lshl_add_u64 v[28:29], v[30:31], 0, v[54:55]
	v_mad_i32_i24 v35, v33, s87, v35
	global_load_dwordx4 v[28:31], v[28:29], off
	v_lshl_add_u64 v[32:33], v[34:35], 0, v[56:57]
	global_load_dwordx4 v[32:35], v[32:33], off
	v_sub_f32_e32 v73, 0xf149f2ca, v72
	v_exp_f32_e32 v73, v73
	v_sub_f32_e32 v36, v36, v158
	v_sub_f32_e32 v37, v37, v158
	v_sub_f32_e32 v38, v38, v158
	v_sub_f32_e32 v39, v39, v158
	v_sub_f32_e32 v40, v40, v158
	v_sub_f32_e32 v41, v41, v158
	v_sub_f32_e32 v42, v42, v158
	v_sub_f32_e32 v43, v43, v158
	v_sub_f32_e32 v44, v44, v158
	v_sub_f32_e32 v45, v45, v158
	v_sub_f32_e32 v46, v46, v158
	v_sub_f32_e32 v47, v47, v158
	v_exp_f32_e32 v138, v36
	v_exp_f32_e32 v228, v37
	v_exp_f32_e32 v139, v38
	v_exp_f32_e32 v213, v39
	v_exp_f32_e32 v144, v40
	v_exp_f32_e32 v147, v41
	v_exp_f32_e32 v145, v42
	v_exp_f32_e32 v146, v43
	v_exp_f32_e32 v141, v44
	v_exp_f32_e32 v143, v45
	v_exp_f32_e32 v140, v46
	v_exp_f32_e32 v142, v47
	s_waitcnt vmcnt(0)
	s_addk_i32 s16, 0x4000
	s_waitcnt vmcnt(4)
	ds_write_b128 v182, v[16:19] offset:16384
	s_waitcnt vmcnt(3)
	ds_write_b128 v183, v[20:23] offset:16384
	s_waitcnt vmcnt(2)
	ds_write_b128 v184, v[24:27] offset:57344
	s_waitcnt vmcnt(1)
	ds_write_b128 v185, v[28:31] offset:57344
	s_waitcnt vmcnt(0)
	ds_write_b128 v186, v[32:35] offset:57344
	v_add_u32_e32 v175, s16, v58
	v_mov_b64_e32 v[46:47], v[14:15]
	v_mov_b64_e32 v[30:31], v[14:15]
	v_mov_b64_e32 v[62:63], v[14:15]
	v_cndmask_b32_e64 v200, v73, 1.0, vcc
	s_add_i32 s15, s4, 0x80
	s_sub_i32 s14, s14, 64
	v_mov_b64_e32 v[44:45], v[12:13]
	v_mov_b64_e32 v[42:43], v[10:11]
	v_mov_b64_e32 v[40:41], v[8:9]
	v_mov_b64_e32 v[38:39], v[6:7]
	v_mov_b64_e32 v[36:37], v[4:5]
	v_mov_b64_e32 v[34:35], v[2:3]
	v_mov_b64_e32 v[32:33], v[0:1]
	v_mov_b64_e32 v[28:29], v[12:13]
	v_mov_b64_e32 v[26:27], v[10:11]
	v_mov_b64_e32 v[24:25], v[8:9]
	v_mov_b64_e32 v[22:23], v[6:7]
	v_mov_b64_e32 v[20:21], v[4:5]
	v_mov_b64_e32 v[18:19], v[2:3]
	v_mov_b64_e32 v[16:17], v[0:1]
	v_mov_b64_e32 v[60:61], v[12:13]
	v_mov_b64_e32 v[58:59], v[10:11]
	v_mov_b64_e32 v[56:57], v[8:9]
	v_mov_b64_e32 v[54:55], v[6:7]
	v_mov_b64_e32 v[52:53], v[4:5]
	v_mov_b64_e32 v[50:51], v[2:3]
	v_mov_b64_e32 v[48:49], v[0:1]
	s_waitcnt lgkmcnt(0)
	s_barrier
	v_lshlrev_b64 v[148:149], 11, v[148:149]
	v_lshlrev_b64 v[156:157], 11, v[156:157]
	v_lshl_add_u64 v[148:149], v[160:161], 0, v[148:149]
	v_lshl_add_u64 v[156:157], v[160:161], 0, v[156:157]
	v_mad_u64_u32 v[150:151], s[74:75], v150, s87, v[162:163]
	v_mad_u64_u32 v[152:153], s[74:75], v152, s87, v[164:165]
	v_mad_u64_u32 v[154:155], s[74:75], v154, s87, v[166:167]
.LBB0_563:
	s_add_i32 s16, s13, -1
	ds_read_b128 v[64:67], v187 offset:57344
	ds_read_b128 v[68:71], v202 offset:57344
	ds_read_b128 v[220:223], v189 offset:57344
	ds_read_b128 v[232:235], v201 offset:57344
	v_add_f32_e32 v178, 0, v136
	v_add_f32_e32 v178, v230, v178
	s_waitcnt lgkmcnt(3)
	v_mfma_f32_32x32x16_bf16 v[80:95], v[64:67], v[96:99], 0
	v_add_f32_e32 v178, v137, v178
	v_add_f32_e32 v178, v229, v178
	v_add_f32_e32 v178, v138, v178
	v_add_f32_e32 v178, v228, v178
	v_add_f32_e32 v178, v139, v178
	v_add_f32_e32 v178, v213, v178
	v_add_f32_e32 v178, v144, v178
	s_waitcnt lgkmcnt(2)
	v_mfma_f32_32x32x16_bf16 v[64:79], v[68:71], v[96:99], 0
	v_add_f32_e32 v178, v147, v178
	v_add_f32_e32 v178, v145, v178
	v_add_f32_e32 v178, v146, v178
	v_exp_f32_e32 v132, v132
	v_add_f32_e32 v178, v141, v178
	v_exp_f32_e32 v133, v133
	v_add_f32_e32 v178, v143, v178
	s_waitcnt lgkmcnt(1)
	v_mfma_f32_32x32x16_bf16 v[80:95], v[220:223], v[100:103], v[80:95]
	v_exp_f32_e32 v134, v134
	v_add_f32_e32 v178, v140, v178
	v_exp_f32_e32 v135, v135
	v_add_f32_e32 v178, v142, v178
	v_exp_f32_e32 v124, v124
	v_add_f32_e32 v178, v132, v178
	v_exp_f32_e32 v125, v125
	s_waitcnt lgkmcnt(0)
	v_mfma_f32_32x32x16_bf16 v[64:79], v[232:235], v[100:103], v[64:79]
	ds_read_b128 v[220:223], v190 offset:57344
	ds_read_b128 v[232:235], v209 offset:57344
	v_add_f32_e32 v178, v133, v178
	v_exp_f32_e32 v126, v126
	v_add_f32_e32 v178, v134, v178
	v_exp_f32_e32 v127, v127
	v_add_f32_e32 v178, v135, v178
	v_exp_f32_e32 v128, v128
	s_waitcnt lgkmcnt(1)
	v_mfma_f32_32x32x16_bf16 v[80:95], v[220:223], v[104:107], v[80:95]
	v_add_f32_e32 v178, v124, v178
	v_exp_f32_e32 v129, v129
	v_add_f32_e32 v178, v125, v178
	v_exp_f32_e32 v130, v130
	v_add_f32_e32 v178, v126, v178
	v_exp_f32_e32 v131, v131
	v_add_f32_e32 v178, v127, v178
	s_waitcnt lgkmcnt(0)
	v_mfma_f32_32x32x16_bf16 v[64:79], v[232:235], v[104:107], v[64:79]
	ds_read_b128 v[220:223], v191 offset:57344
	ds_read_b128 v[232:235], v212 offset:57344
	v_exp_f32_e32 v120, v120
	v_add_f32_e32 v178, v128, v178
	v_exp_f32_e32 v121, v121
	v_add_f32_e32 v178, v129, v178
	v_exp_f32_e32 v122, v122
	v_add_f32_e32 v178, v130, v178
	s_waitcnt lgkmcnt(1)
	v_mfma_f32_32x32x16_bf16 v[80:95], v[220:223], v[108:111], v[80:95]
	v_exp_f32_e32 v123, v123
	v_add_f32_e32 v178, v131, v178
	v_add_f32_e32 v178, v120, v178
	v_add_f32_e32 v178, v121, v178
	v_add_f32_e32 v178, v122, v178
	v_add_f32_e32 v231, v123, v178
	s_waitcnt lgkmcnt(0)
	v_mfma_f32_32x32x16_bf16 v[64:79], v[232:235], v[108:111], v[64:79]
	ds_read_b128 v[220:223], v192 offset:57344
	ds_read_b128 v[232:235], v211 offset:57344
	s_waitcnt lgkmcnt(1)
	v_mfma_f32_32x32x16_bf16 v[80:95], v[220:223], v[112:115], v[80:95]
	s_waitcnt lgkmcnt(0)
	v_mfma_f32_32x32x16_bf16 v[64:79], v[232:235], v[112:115], v[64:79]
	ds_read_b128 v[220:223], v193 offset:57344
	ds_read_b128 v[232:235], v210 offset:57344
	s_waitcnt lgkmcnt(1)
	v_mfma_f32_32x32x16_bf16 v[80:95], v[220:223], v[116:119], v[80:95]
	s_waitcnt lgkmcnt(0)
	v_mfma_f32_32x32x16_bf16 v[64:79], v[232:235], v[116:119], v[64:79]
	ds_read_b128 v[220:223], v194 offset:57344
	ds_read_b128 v[232:235], v208 offset:57344
	ds_read_b128 v[236:239], v171
	s_waitcnt lgkmcnt(0)
	v_mfma_f32_32x32x16_bf16 v[80:95], v[220:223], v[236:239], v[80:95]
	v_mfma_f32_32x32x16_bf16 v[64:79], v[232:235], v[236:239], v[64:79]
	ds_read_b128 v[220:223], v195 offset:57344
	ds_read_b128 v[232:235], v207 offset:57344
	ds_read_b128 v[236:239], v171 offset:1024
	s_waitcnt lgkmcnt(0)
	v_mfma_f32_32x32x16_bf16 v[80:95], v[220:223], v[236:239], v[80:95]
	v_mfma_f32_32x32x16_bf16 v[64:79], v[232:235], v[236:239], v[64:79]
	ds_read_b128 v[220:223], v196 offset:57344
	ds_read_b128 v[232:235], v206 offset:57344
	ds_read_b128 v[236:239], v171 offset:2048
	s_waitcnt lgkmcnt(0)
	v_mfma_f32_32x32x16_bf16 v[80:95], v[220:223], v[236:239], v[80:95]
	v_mfma_f32_32x32x16_bf16 v[64:79], v[232:235], v[236:239], v[64:79]
	ds_read_b128 v[220:223], v197 offset:57344
	ds_read_b128 v[232:235], v205 offset:57344
	ds_read_b128 v[236:239], v171 offset:3072
	s_waitcnt lgkmcnt(0)
	v_mfma_f32_32x32x16_bf16 v[80:95], v[220:223], v[236:239], v[80:95]
	v_mfma_f32_32x32x16_bf16 v[64:79], v[232:235], v[236:239], v[64:79]
	ds_read_b128 v[220:223], v199 offset:57344
	ds_read_b128 v[232:235], v204 offset:57344
	ds_read_b128 v[236:239], v171 offset:4096
	s_waitcnt lgkmcnt(0)
	v_mfma_f32_32x32x16_bf16 v[80:95], v[220:223], v[236:239], v[80:95]
	v_mfma_f32_32x32x16_bf16 v[64:79], v[232:235], v[236:239], v[64:79]
	ds_read_b128 v[220:223], v198 offset:57344
	ds_read_b128 v[232:235], v203 offset:57344
	ds_read_b128 v[236:239], v171 offset:5120
	v_cvt_pk_bf16_f32 v136, v136, v230
	v_cvt_pk_bf16_f32 v137, v137, v229
	v_cvt_pk_bf16_f32 v138, v138, v228
	v_cvt_pk_bf16_f32 v139, v139, v213
	v_cvt_pk_bf16_f32 v144, v144, v147
	v_cvt_pk_bf16_f32 v145, v145, v146
	s_waitcnt lgkmcnt(0)
	v_mfma_f32_32x32x16_bf16 v[80:95], v[220:223], v[236:239], v[80:95]
	v_cvt_pk_bf16_f32 v146, v141, v143
	v_cvt_pk_bf16_f32 v147, v140, v142
	v_cvt_pk_bf16_f32 v220, v132, v133
	v_cvt_pk_bf16_f32 v221, v134, v135
	v_cvt_pk_bf16_f32 v222, v124, v125
	v_cvt_pk_bf16_f32 v223, v126, v127
	v_permlane32_swap_b32_e32 v136, v138
	v_mfma_f32_32x32x16_bf16 v[64:79], v[232:235], v[236:239], v[64:79]
	v_mov_b32_e32 v233, v231
	v_cvt_pk_bf16_f32 v234, v128, v129
	v_cvt_pk_bf16_f32 v235, v130, v131
	v_cvt_pk_bf16_f32 v236, v120, v121
	s_nop 1
	v_permlane32_swap_b32_e32 v231, v233
	v_cvt_pk_bf16_f32 v237, v122, v123
	v_permlane32_swap_b32_e32 v234, v236
	v_permlane32_swap_b32_e32 v137, v139
	v_permlane32_swap_b32_e32 v144, v146
	v_permlane32_swap_b32_e32 v145, v147
	v_permlane32_swap_b32_e32 v220, v222
	v_permlane32_swap_b32_e32 v221, v223
	v_permlane32_swap_b32_e32 v235, v237
	s_sub_i32 s4, s14, 64
	s_cmp_lt_u32 s16, 3
	s_cselect_b32 s4, s15, s4
	s_ashr_i32 s5, s4, 31
	s_lshl_b64 s[76:77], s[4:5], 11
	s_mul_hi_i32 s79, s4, s87
	s_mul_i32 s78, s4, s87
	v_lshl_add_u64 v[120:121], v[148:149], 0, s[76:77]
	v_lshl_add_u64 v[124:125], v[156:157], 0, s[76:77]
	v_lshl_add_u64 v[130:131], v[150:151], 0, s[78:79]
	v_lshl_add_u64 v[134:135], v[152:153], 0, s[78:79]
	v_lshl_add_u64 v[140:141], v[154:155], 0, s[78:79]
	global_load_dwordx4 v[120:123], v[120:121], off
	s_nop 0
	global_load_dwordx4 v[124:127], v[124:125], off
	s_nop 0
	global_load_dwordx4 v[128:131], v[130:131], off
	s_nop 0
	global_load_dwordx4 v[132:135], v[134:135], off
	s_nop 0
	global_load_dwordx4 v[140:143], v[140:141], off
	ds_read_b64_tr_b16 v[238:239], v172 offset:0
	ds_read_b64_tr_b16 v[240:241], v172 offset:0x800
	ds_read_b64_tr_b16 v[242:243], v172 offset:0x1000
	ds_read_b64_tr_b16 v[244:245], v172 offset:0x1800
	ds_read_b64_tr_b16 v[246:247], v172 offset:0x2000
	ds_read_b64_tr_b16 v[248:249], v172 offset:0x2800
	ds_read_b64_tr_b16 v[250:251], v172 offset:0x3000
	ds_read_b64_tr_b16 v[252:253], v172 offset:0x3800
	s_waitcnt lgkmcnt(0)
	s_nop 0
	v_mfma_f32_32x32x16_bf16 v[0:15], v[136:139], v[238:241], v[0:15]
	ds_read_b64_tr_b16 v[238:239], v172 offset:0x200
	ds_read_b64_tr_b16 v[240:241], v172 offset:0xa00
	v_mfma_f32_32x32x16_bf16 v[0:15], v[144:147], v[242:245], v[0:15]
	ds_read_b64_tr_b16 v[242:243], v172 offset:0x1200
	ds_read_b64_tr_b16 v[244:245], v172 offset:0x1a00
	v_mfma_f32_32x32x16_bf16 v[0:15], v[220:223], v[246:249], v[0:15]
	ds_read_b64_tr_b16 v[246:247], v172 offset:0x2200
	ds_read_b64_tr_b16 v[248:249], v172 offset:0x2a00
	v_mfma_f32_32x32x16_bf16 v[0:15], v[234:237], v[250:253], v[0:15]
	ds_read_b64_tr_b16 v[250:251], v172 offset:0x3200
	ds_read_b64_tr_b16 v[252:253], v172 offset:0x3a00
	s_waitcnt lgkmcnt(0)
	v_mfma_f32_32x32x16_bf16 v[32:47], v[136:139], v[238:241], v[32:47]
	ds_read_b64_tr_b16 v[238:239], v172 offset:0x400
	ds_read_b64_tr_b16 v[240:241], v172 offset:0xc00
	v_mfma_f32_32x32x16_bf16 v[32:47], v[144:147], v[242:245], v[32:47]
	ds_read_b64_tr_b16 v[242:243], v172 offset:0x1400
	ds_read_b64_tr_b16 v[244:245], v172 offset:0x1c00
	v_mfma_f32_32x32x16_bf16 v[32:47], v[220:223], v[246:249], v[32:47]
	ds_read_b64_tr_b16 v[246:247], v172 offset:0x2400
	ds_read_b64_tr_b16 v[248:249], v172 offset:0x2c00
	v_mfma_f32_32x32x16_bf16 v[32:47], v[234:237], v[250:253], v[32:47]
	ds_read_b64_tr_b16 v[250:251], v172 offset:0x3400
	ds_read_b64_tr_b16 v[252:253], v172 offset:0x3c00
	s_waitcnt lgkmcnt(0)
	v_mfma_f32_32x32x16_bf16 v[16:31], v[136:139], v[238:241], v[16:31]
	ds_read_b64_tr_b16 v[238:239], v172 offset:0x600
	ds_read_b64_tr_b16 v[240:241], v172 offset:0xe00
	v_mfma_f32_32x32x16_bf16 v[16:31], v[144:147], v[242:245], v[16:31]
	ds_read_b64_tr_b16 v[242:243], v172 offset:0x1600
	ds_read_b64_tr_b16 v[244:245], v172 offset:0x1e00
	v_mfma_f32_32x32x16_bf16 v[16:31], v[220:223], v[246:249], v[16:31]
	ds_read_b64_tr_b16 v[246:247], v172 offset:0x2600
	ds_read_b64_tr_b16 v[248:249], v172 offset:0x2e00
	v_mfma_f32_32x32x16_bf16 v[16:31], v[234:237], v[250:253], v[16:31]
	ds_read_b64_tr_b16 v[250:251], v172 offset:0x3600
	ds_read_b64_tr_b16 v[252:253], v172 offset:0x3e00
	s_waitcnt lgkmcnt(0)
	v_mfma_f32_32x32x16_bf16 v[48:63], v[136:139], v[238:241], v[48:63]
	v_max_f32_e32 v136, v81, v81
	v_max_f32_e32 v137, v80, v80
	v_max_f32_e32 v136, v137, v136
	v_max3_f32 v136, v136, v82, v83
	v_max3_f32 v136, v136, v84, v85
	v_max3_f32 v136, v136, v86, v87
	v_max3_f32 v136, v136, v88, v89
	v_max3_f32 v136, v136, v90, v91
	v_mfma_f32_32x32x16_bf16 v[48:63], v[144:147], v[242:245], v[48:63]
	v_max3_f32 v136, v136, v92, v93
	v_max3_f32 v136, v136, v94, v95
	v_max3_f32 v136, v136, v64, v65
	v_max3_f32 v136, v136, v66, v67
	v_max3_f32 v136, v136, v68, v69
	v_max3_f32 v136, v136, v70, v71
	v_max3_f32 v136, v136, v72, v73
	v_max3_f32 v136, v136, v74, v75
	v_mfma_f32_32x32x16_bf16 v[48:63], v[220:223], v[246:249], v[48:63]
	v_max3_f32 v136, v136, v76, v77
	v_max3_f32 v136, v136, v78, v79
	v_mov_b32_e32 v137, v136
	s_nop 1
	v_permlane32_swap_b32_e32 v136, v137
	v_max_f32_e32 v137, v137, v137
	v_max_f32_e32 v136, v136, v136
	v_max_f32_e32 v136, v136, v137
	v_sub_f32_e32 v137, v136, v158
	v_cmp_ge_f32_e32 vcc, s90, v137
	v_max_f32_e32 v137, v158, v158
	v_mfma_f32_32x32x16_bf16 v[48:63], v[234:237], v[250:253], v[48:63]
	v_max_f32_e32 v136, v137, v136
	v_sub_f32_e32 v137, v158, v136
	v_exp_f32_e32 v137, v137
	s_cmp_eq_u64 vcc, exec
	s_cselect_b64 s[4:5], -1, 0
	s_barrier
	s_waitcnt vmcnt(0)
	v_cndmask_b32_e64 v234, v137, 1.0, s[4:5]
	v_cmp_gt_f32_e32 vcc, 1.0, v234
	s_waitcnt vmcnt(4)
	ds_write_b128 v182, v[120:123]
	s_waitcnt vmcnt(3)
	ds_write_b128 v183, v[124:127]
	s_waitcnt vmcnt(2)
	ds_write_b128 v184, v[128:131] offset:32768
	s_waitcnt vmcnt(1)
	ds_write_b128 v185, v[132:135] offset:32768
	s_waitcnt vmcnt(0)
	ds_write_b128 v186, v[140:143] offset:32768
	s_cbranch_vccz .LBB0_567
	s_and_saveexec_b64 s[6:7], s[2:3]
	ds_write_b32 v173, v234 offset:128
	s_or_b64 exec, exec, s[6:7]
	s_waitcnt lgkmcnt(0)
	v_add_u32_e32 v132, v169, v176
	ds_read_b128 v[120:123], v132 offset:224
	ds_read_b128 v[124:127], v132 offset:192
	ds_read_b128 v[128:131], v132 offset:160
	ds_read_b128 v[132:135], v132 offset:128
	s_waitcnt lgkmcnt(3)
	v_pk_mul_f32 v[12:13], v[12:13], v[120:121]
	s_waitcnt lgkmcnt(2)
	v_pk_mul_f32 v[8:9], v[8:9], v[124:125]
	s_waitcnt lgkmcnt(1)
	v_pk_mul_f32 v[4:5], v[4:5], v[128:129]
	v_pk_mul_f32 v[14:15], v[14:15], v[122:123]
	v_pk_mul_f32 v[10:11], v[10:11], v[126:127]
	v_pk_mul_f32 v[6:7], v[6:7], v[130:131]
	s_waitcnt lgkmcnt(0)
	v_pk_mul_f32 v[2:3], v[2:3], v[134:135]
	v_pk_mul_f32 v[0:1], v[0:1], v[132:133]
	v_pk_mul_f32 v[44:45], v[44:45], v[120:121]
	v_pk_mul_f32 v[40:41], v[40:41], v[124:125]
	v_pk_mul_f32 v[36:37], v[36:37], v[128:129]
	v_pk_mul_f32 v[46:47], v[46:47], v[122:123]
	v_pk_mul_f32 v[42:43], v[42:43], v[126:127]
	v_pk_mul_f32 v[38:39], v[38:39], v[130:131]
	v_pk_mul_f32 v[34:35], v[34:35], v[134:135]
	v_pk_mul_f32 v[32:33], v[32:33], v[132:133]
	v_pk_mul_f32 v[28:29], v[28:29], v[120:121]
	v_pk_mul_f32 v[24:25], v[24:25], v[124:125]
	v_pk_mul_f32 v[20:21], v[20:21], v[128:129]
	v_pk_mul_f32 v[30:31], v[30:31], v[122:123]
	v_pk_mul_f32 v[26:27], v[26:27], v[126:127]
	v_pk_mul_f32 v[22:23], v[22:23], v[130:131]
	v_pk_mul_f32 v[18:19], v[18:19], v[134:135]
	v_pk_mul_f32 v[16:17], v[16:17], v[132:133]
	v_pk_mul_f32 v[60:61], v[60:61], v[120:121]
	v_pk_mul_f32 v[56:57], v[56:57], v[124:125]
	v_pk_mul_f32 v[52:53], v[52:53], v[128:129]
	v_pk_mul_f32 v[62:63], v[62:63], v[122:123]
	v_pk_mul_f32 v[58:59], v[58:59], v[126:127]
	v_pk_mul_f32 v[54:55], v[54:55], v[130:131]
	v_pk_mul_f32 v[50:51], v[50:51], v[134:135]
	v_pk_mul_f32 v[48:49], v[48:49], v[132:133]
.LBB0_567:
	v_cndmask_b32_e64 v158, v136, v158, s[4:5]
	v_sub_f32_e32 v80, v80, v158
	v_sub_f32_e32 v81, v81, v158
	v_sub_f32_e32 v82, v82, v158
	v_sub_f32_e32 v83, v83, v158
	v_sub_f32_e32 v84, v84, v158
	v_sub_f32_e32 v85, v85, v158
	v_sub_f32_e32 v86, v86, v158
	v_sub_f32_e32 v87, v87, v158
	v_sub_f32_e32 v88, v88, v158
	v_sub_f32_e32 v89, v89, v158
	v_sub_f32_e32 v90, v90, v158
	v_sub_f32_e32 v91, v91, v158
	v_sub_f32_e32 v92, v92, v158
	v_sub_f32_e32 v93, v93, v158
	v_sub_f32_e32 v94, v94, v158
	v_sub_f32_e32 v95, v95, v158
	v_sub_f32_e32 v232, v76, v158
	v_sub_f32_e32 v235, v77, v158
	v_sub_f32_e32 v236, v78, v158
	v_exp_f32_e32 v133, v80
	v_exp_f32_e32 v135, v81
	v_exp_f32_e32 v131, v82
	v_exp_f32_e32 v134, v83
	v_exp_f32_e32 v130, v84
	v_exp_f32_e32 v132, v85
	v_exp_f32_e32 v128, v86
	v_exp_f32_e32 v129, v87
	v_exp_f32_e32 v125, v88
	v_exp_f32_e32 v127, v89
	v_exp_f32_e32 v124, v90
	v_exp_f32_e32 v126, v91
	v_exp_f32_e32 v121, v92
	v_exp_f32_e32 v123, v93
	v_exp_f32_e32 v120, v94
	v_exp_f32_e32 v122, v95
	v_sub_f32_e32 v178, v64, v158
	v_sub_f32_e32 v179, v65, v158
	v_sub_f32_e32 v213, v66, v158
	v_sub_f32_e32 v220, v67, v158
	v_sub_f32_e32 v221, v68, v158
	v_sub_f32_e32 v222, v69, v158
	v_sub_f32_e32 v223, v70, v158
	v_sub_f32_e32 v226, v71, v158
	v_sub_f32_e32 v227, v72, v158
	v_sub_f32_e32 v228, v73, v158
	v_sub_f32_e32 v229, v74, v158
	v_sub_f32_e32 v230, v75, v158
	v_sub_f32_e32 v237, v79, v158
	s_waitcnt lgkmcnt(0)
	s_barrier
	ds_read_b128 v[64:67], v187 offset:32768
	ds_read_b128 v[68:71], v187 offset:45056
	ds_read_b128 v[136:139], v189 offset:32768
	ds_read_b128 v[140:143], v189 offset:45056
	v_exp_f32_e32 v241, v236
	v_exp_f32_e32 v237, v237
	s_waitcnt lgkmcnt(3)
	v_mfma_f32_32x32x16_bf16 v[80:95], v[64:67], v[96:99], 0
	s_waitcnt lgkmcnt(2)
	v_mfma_f32_32x32x16_bf16 v[64:79], v[68:71], v[96:99], 0
	s_waitcnt lgkmcnt(1)
	v_mfma_f32_32x32x16_bf16 v[80:95], v[136:139], v[100:103], v[80:95]
	s_waitcnt lgkmcnt(0)
	v_mfma_f32_32x32x16_bf16 v[64:79], v[140:143], v[100:103], v[64:79]
	ds_read_b128 v[136:139], v190 offset:32768
	ds_read_b128 v[140:143], v190 offset:45056
	s_waitcnt lgkmcnt(1)
	v_mfma_f32_32x32x16_bf16 v[80:95], v[136:139], v[104:107], v[80:95]
	s_waitcnt lgkmcnt(0)
	v_mfma_f32_32x32x16_bf16 v[64:79], v[140:143], v[104:107], v[64:79]
	ds_read_b128 v[136:139], v191 offset:32768
	ds_read_b128 v[140:143], v191 offset:45056
	s_waitcnt lgkmcnt(1)
	v_mfma_f32_32x32x16_bf16 v[80:95], v[136:139], v[108:111], v[80:95]
	s_waitcnt lgkmcnt(0)
	v_mfma_f32_32x32x16_bf16 v[64:79], v[140:143], v[108:111], v[64:79]
	ds_read_b128 v[136:139], v192 offset:32768
	ds_read_b128 v[140:143], v192 offset:45056
	s_waitcnt lgkmcnt(1)
	v_mfma_f32_32x32x16_bf16 v[80:95], v[136:139], v[112:115], v[80:95]
	s_waitcnt lgkmcnt(0)
	v_mfma_f32_32x32x16_bf16 v[64:79], v[140:143], v[112:115], v[64:79]
	ds_read_b128 v[136:139], v193 offset:32768
	ds_read_b128 v[140:143], v193 offset:45056
	s_waitcnt lgkmcnt(1)
	v_mfma_f32_32x32x16_bf16 v[80:95], v[136:139], v[116:119], v[80:95]
	s_waitcnt lgkmcnt(0)
	v_mfma_f32_32x32x16_bf16 v[64:79], v[140:143], v[116:119], v[64:79]
	ds_read_b128 v[136:139], v194 offset:32768
	ds_read_b128 v[140:143], v194 offset:45056
	ds_read_b128 v[144:147], v171
	s_waitcnt lgkmcnt(0)
	v_mfma_f32_32x32x16_bf16 v[80:95], v[136:139], v[144:147], v[80:95]
	v_mfma_f32_32x32x16_bf16 v[64:79], v[140:143], v[144:147], v[64:79]
	ds_read_b128 v[136:139], v195 offset:32768
	ds_read_b128 v[140:143], v195 offset:45056
	ds_read_b128 v[144:147], v171 offset:1024
	s_waitcnt lgkmcnt(0)
	v_mfma_f32_32x32x16_bf16 v[80:95], v[136:139], v[144:147], v[80:95]
	v_mfma_f32_32x32x16_bf16 v[64:79], v[140:143], v[144:147], v[64:79]
	ds_read_b128 v[136:139], v196 offset:32768
	ds_read_b128 v[140:143], v196 offset:45056
	ds_read_b128 v[144:147], v171 offset:2048
	s_waitcnt lgkmcnt(0)
	v_mfma_f32_32x32x16_bf16 v[80:95], v[136:139], v[144:147], v[80:95]
	v_mfma_f32_32x32x16_bf16 v[64:79], v[140:143], v[144:147], v[64:79]
	ds_read_b128 v[136:139], v197 offset:32768
	ds_read_b128 v[140:143], v197 offset:45056
	ds_read_b128 v[144:147], v171 offset:3072
	s_waitcnt lgkmcnt(0)
	v_mfma_f32_32x32x16_bf16 v[80:95], v[136:139], v[144:147], v[80:95]
	v_mfma_f32_32x32x16_bf16 v[64:79], v[140:143], v[144:147], v[64:79]
	ds_read_b128 v[136:139], v199 offset:32768
	ds_read_b128 v[140:143], v199 offset:45056
	ds_read_b128 v[144:147], v171 offset:4096
	s_waitcnt lgkmcnt(0)
	v_mfma_f32_32x32x16_bf16 v[80:95], v[136:139], v[144:147], v[80:95]
	v_mfma_f32_32x32x16_bf16 v[64:79], v[140:143], v[144:147], v[64:79]
	ds_read_b128 v[136:139], v198 offset:32768
	ds_read_b128 v[140:143], v198 offset:45056
	ds_read_b128 v[144:147], v171 offset:5120
	s_waitcnt lgkmcnt(0)
	v_mfma_f32_32x32x16_bf16 v[80:95], v[136:139], v[144:147], v[80:95]
	v_add_f32_e32 v136, 0, v133
	v_add_f32_e32 v136, v135, v136
	v_add_f32_e32 v136, v131, v136
	v_add_f32_e32 v136, v134, v136
	v_add_f32_e32 v136, v130, v136
	v_add_f32_e32 v136, v132, v136
	v_add_f32_e32 v136, v128, v136
	v_add_f32_e32 v136, v129, v136
	v_add_f32_e32 v136, v125, v136
	v_add_f32_e32 v136, v127, v136
	v_add_f32_e32 v136, v124, v136
	v_add_f32_e32 v136, v126, v136
	v_mfma_f32_32x32x16_bf16 v[64:79], v[140:143], v[144:147], v[64:79]
	v_exp_f32_e32 v140, v178
	v_add_f32_e32 v136, v121, v136
	v_exp_f32_e32 v141, v179
	v_add_f32_e32 v136, v123, v136
	v_exp_f32_e32 v142, v213
	v_add_f32_e32 v136, v120, v136
	v_exp_f32_e32 v143, v220
	v_add_f32_e32 v136, v122, v136
	v_exp_f32_e32 v178, v221
	v_add_f32_e32 v136, v140, v136
	v_exp_f32_e32 v179, v222
	v_add_f32_e32 v136, v141, v136
	v_exp_f32_e32 v213, v223
	v_add_f32_e32 v136, v142, v136
	v_exp_f32_e32 v223, v226
	v_add_f32_e32 v136, v143, v136
	v_exp_f32_e32 v226, v227
	v_add_f32_e32 v136, v178, v136
	v_exp_f32_e32 v227, v228
	v_add_f32_e32 v136, v179, v136
	v_exp_f32_e32 v228, v229
	v_add_f32_e32 v136, v213, v136
	v_exp_f32_e32 v229, v230
	v_add_f32_e32 v136, v223, v136
	v_exp_f32_e32 v230, v232
	v_add_f32_e32 v136, v226, v136
	v_exp_f32_e32 v232, v235
	v_add_f32_e32 v136, v227, v136
	v_add_f32_e32 v136, v228, v136
	v_add_f32_e32 v136, v229, v136
	v_add_f32_e32 v136, v230, v136
	v_add_f32_e32 v136, v232, v136
	v_add_f32_e32 v136, v241, v136
	v_add_f32_e32 v235, v237, v136
	v_mov_b32_e32 v236, v235
	v_cvt_pk_bf16_f32 v136, v133, v135
	v_cvt_pk_bf16_f32 v137, v131, v134
	v_cvt_pk_bf16_f32 v138, v130, v132
	s_nop 1
	v_permlane32_swap_b32_e32 v235, v236
	v_cvt_pk_bf16_f32 v139, v128, v129
	v_permlane32_swap_b32_e32 v136, v138
	v_cvt_pk_bf16_f32 v144, v125, v127
	v_cvt_pk_bf16_f32 v145, v124, v126
	v_cvt_pk_bf16_f32 v146, v121, v123
	v_cvt_pk_bf16_f32 v147, v120, v122
	v_cvt_pk_bf16_f32 v220, v140, v141
	v_cvt_pk_bf16_f32 v221, v142, v143
	v_cvt_pk_bf16_f32 v222, v178, v179
	v_cvt_pk_bf16_f32 v223, v213, v223
	v_cvt_pk_bf16_f32 v238, v226, v227
	v_cvt_pk_bf16_f32 v239, v228, v229
	v_cvt_pk_bf16_f32 v240, v230, v232
	v_cvt_pk_bf16_f32 v241, v241, v237
	v_permlane32_swap_b32_e32 v137, v139
	v_permlane32_swap_b32_e32 v144, v146
	v_permlane32_swap_b32_e32 v145, v147
	v_permlane32_swap_b32_e32 v220, v222
	v_permlane32_swap_b32_e32 v221, v223
	v_permlane32_swap_b32_e32 v238, v240
	v_permlane32_swap_b32_e32 v239, v241
	s_add_i32 s4, s15, 64
	s_cmp_lt_u32 s16, 2
	s_cselect_b32 s4, s4, s14
	s_ashr_i32 s5, s4, 31
	s_lshl_b64 s[76:77], s[4:5], 11
	s_mul_hi_i32 s79, s4, s87
	s_mul_i32 s78, s4, s87
	v_lshl_add_u64 v[120:121], v[148:149], 0, s[76:77]
	v_lshl_add_u64 v[124:125], v[156:157], 0, s[76:77]
	v_lshl_add_u64 v[130:131], v[150:151], 0, s[78:79]
	v_lshl_add_u64 v[134:135], v[152:153], 0, s[78:79]
	v_lshl_add_u64 v[140:141], v[154:155], 0, s[78:79]
	global_load_dwordx4 v[120:123], v[120:121], off
	s_nop 0
	global_load_dwordx4 v[124:127], v[124:125], off
	s_nop 0
	global_load_dwordx4 v[128:131], v[130:131], off
	s_nop 0
	global_load_dwordx4 v[132:135], v[134:135], off
	s_nop 0
	global_load_dwordx4 v[140:143], v[140:141], off
	ds_read_b64_tr_b16 v[242:243], v175 offset:0
	ds_read_b64_tr_b16 v[244:245], v175 offset:0x800
	ds_read_b64_tr_b16 v[246:247], v175 offset:0x1000
	ds_read_b64_tr_b16 v[248:249], v175 offset:0x1800
	ds_read_b64_tr_b16 v[250:251], v175 offset:0x2000
	ds_read_b64_tr_b16 v[252:253], v175 offset:0x2800
	ds_read_b64_tr_b16 v[226:227], v175 offset:0x3000
	ds_read_b64_tr_b16 v[228:229], v175 offset:0x3800
	s_waitcnt lgkmcnt(0)
	s_nop 0
	v_mfma_f32_32x32x16_bf16 v[0:15], v[136:139], v[242:245], v[0:15]
	v_mfma_f32_32x32x16_bf16 v[0:15], v[144:147], v[246:249], v[0:15]
	v_mfma_f32_32x32x16_bf16 v[0:15], v[220:223], v[250:253], v[0:15]
	v_mfma_f32_32x32x16_bf16 v[0:15], v[238:241], v[226:229], v[0:15]
	ds_read_b64_tr_b16 v[226:227], v175 offset:0x200
	ds_read_b64_tr_b16 v[228:229], v175 offset:0xa00
	ds_read_b64_tr_b16 v[242:243], v175 offset:0x1200
	ds_read_b64_tr_b16 v[244:245], v175 offset:0x1a00
	ds_read_b64_tr_b16 v[246:247], v175 offset:0x2200
	ds_read_b64_tr_b16 v[248:249], v175 offset:0x2a00
	ds_read_b64_tr_b16 v[250:251], v175 offset:0x3200
	ds_read_b64_tr_b16 v[252:253], v175 offset:0x3a00
	s_waitcnt lgkmcnt(0)
	s_nop 0
	v_mfma_f32_32x32x16_bf16 v[32:47], v[136:139], v[226:229], v[32:47]
	ds_read_b64_tr_b16 v[226:227], v175 offset:0x400
	ds_read_b64_tr_b16 v[228:229], v175 offset:0xc00
	v_mfma_f32_32x32x16_bf16 v[32:47], v[144:147], v[242:245], v[32:47]
	ds_read_b64_tr_b16 v[242:243], v175 offset:0x1400
	ds_read_b64_tr_b16 v[244:245], v175 offset:0x1c00
	v_mfma_f32_32x32x16_bf16 v[32:47], v[220:223], v[246:249], v[32:47]
	ds_read_b64_tr_b16 v[246:247], v175 offset:0x2400
	ds_read_b64_tr_b16 v[248:249], v175 offset:0x2c00
	v_mfma_f32_32x32x16_bf16 v[32:47], v[238:241], v[250:253], v[32:47]
	ds_read_b64_tr_b16 v[250:251], v175 offset:0x3400
	ds_read_b64_tr_b16 v[252:253], v175 offset:0x3c00
	s_waitcnt lgkmcnt(0)
	v_mfma_f32_32x32x16_bf16 v[16:31], v[136:139], v[226:229], v[16:31]
	ds_read_b64_tr_b16 v[226:227], v175 offset:0x600
	ds_read_b64_tr_b16 v[228:229], v175 offset:0xe00
	v_mfma_f32_32x32x16_bf16 v[16:31], v[144:147], v[242:245], v[16:31]
	ds_read_b64_tr_b16 v[242:243], v175 offset:0x1600
	ds_read_b64_tr_b16 v[244:245], v175 offset:0x1e00
	v_mfma_f32_32x32x16_bf16 v[16:31], v[220:223], v[246:249], v[16:31]
	ds_read_b64_tr_b16 v[246:247], v175 offset:0x2600
	ds_read_b64_tr_b16 v[248:249], v175 offset:0x2e00
	v_mfma_f32_32x32x16_bf16 v[16:31], v[238:241], v[250:253], v[16:31]
	ds_read_b64_tr_b16 v[250:251], v175 offset:0x3600
	ds_read_b64_tr_b16 v[252:253], v175 offset:0x3e00
	s_waitcnt lgkmcnt(0)
	v_mfma_f32_32x32x16_bf16 v[48:63], v[136:139], v[226:229], v[48:63]
	v_max_f32_e32 v136, v81, v81
	v_max_f32_e32 v137, v80, v80
	v_max_f32_e32 v136, v137, v136
	v_max3_f32 v136, v136, v82, v83
	v_max3_f32 v136, v136, v84, v85
	v_max3_f32 v136, v136, v86, v87
	v_max3_f32 v136, v136, v88, v89
	v_max3_f32 v136, v136, v90, v91
	v_mfma_f32_32x32x16_bf16 v[48:63], v[144:147], v[242:245], v[48:63]
	v_max3_f32 v136, v136, v92, v93
	v_max3_f32 v136, v136, v94, v95
	v_max3_f32 v136, v136, v64, v65
	v_max3_f32 v136, v136, v66, v67
	v_max3_f32 v136, v136, v68, v69
	v_max3_f32 v136, v136, v70, v71
	v_max3_f32 v136, v136, v72, v73
	v_max3_f32 v136, v136, v74, v75
	v_mfma_f32_32x32x16_bf16 v[48:63], v[220:223], v[246:249], v[48:63]
	v_max3_f32 v136, v136, v76, v77
	v_max3_f32 v136, v136, v78, v79
	v_mov_b32_e32 v137, v136
	s_nop 1
	v_permlane32_swap_b32_e32 v136, v137
	v_max_f32_e32 v137, v137, v137
	v_max_f32_e32 v136, v136, v136
	v_max_f32_e32 v136, v136, v137
	v_sub_f32_e32 v137, v136, v158
	v_cmp_ge_f32_e32 vcc, s90, v137
	v_max_f32_e32 v137, v158, v158
	v_mfma_f32_32x32x16_bf16 v[48:63], v[238:241], v[250:253], v[48:63]
	v_max_f32_e32 v136, v137, v136
	v_sub_f32_e32 v137, v158, v136
	v_exp_f32_e32 v137, v137
	s_cmp_eq_u64 vcc, exec
	s_cselect_b64 s[4:5], -1, 0
	s_barrier
	s_waitcnt vmcnt(0)
	v_cndmask_b32_e64 v232, v137, 1.0, s[4:5]
	v_cmp_gt_f32_e32 vcc, 1.0, v232
	s_waitcnt vmcnt(4)
	ds_write_b128 v182, v[120:123] offset:16384
	s_waitcnt vmcnt(3)
	ds_write_b128 v183, v[124:127] offset:16384
	s_waitcnt vmcnt(2)
	ds_write_b128 v184, v[128:131] offset:57344
	s_waitcnt vmcnt(1)
	ds_write_b128 v185, v[132:135] offset:57344
	s_waitcnt vmcnt(0)
	ds_write_b128 v186, v[140:143] offset:57344
	s_cbranch_vccz .LBB0_571
	s_and_saveexec_b64 s[6:7], s[2:3]
	ds_write_b32 v173, v232 offset:128
	s_or_b64 exec, exec, s[6:7]
	s_waitcnt lgkmcnt(0)
	v_add_u32_e32 v132, v169, v176
	ds_read_b128 v[120:123], v132 offset:224
	ds_read_b128 v[124:127], v132 offset:192
	ds_read_b128 v[128:131], v132 offset:160
	ds_read_b128 v[132:135], v132 offset:128
	s_waitcnt lgkmcnt(3)
	v_pk_mul_f32 v[12:13], v[12:13], v[120:121]
	s_waitcnt lgkmcnt(2)
	v_pk_mul_f32 v[8:9], v[8:9], v[124:125]
	s_waitcnt lgkmcnt(1)
	v_pk_mul_f32 v[4:5], v[4:5], v[128:129]
	v_pk_mul_f32 v[14:15], v[14:15], v[122:123]
	v_pk_mul_f32 v[10:11], v[10:11], v[126:127]
	v_pk_mul_f32 v[6:7], v[6:7], v[130:131]
	s_waitcnt lgkmcnt(0)
	v_pk_mul_f32 v[2:3], v[2:3], v[134:135]
	v_pk_mul_f32 v[0:1], v[0:1], v[132:133]
	v_pk_mul_f32 v[44:45], v[44:45], v[120:121]
	v_pk_mul_f32 v[40:41], v[40:41], v[124:125]
	v_pk_mul_f32 v[36:37], v[36:37], v[128:129]
	v_pk_mul_f32 v[46:47], v[46:47], v[122:123]
	v_pk_mul_f32 v[42:43], v[42:43], v[126:127]
	v_pk_mul_f32 v[38:39], v[38:39], v[130:131]
	v_pk_mul_f32 v[34:35], v[34:35], v[134:135]
	v_pk_mul_f32 v[32:33], v[32:33], v[132:133]
	v_pk_mul_f32 v[28:29], v[28:29], v[120:121]
	v_pk_mul_f32 v[24:25], v[24:25], v[124:125]
	v_pk_mul_f32 v[20:21], v[20:21], v[128:129]
	v_pk_mul_f32 v[30:31], v[30:31], v[122:123]
	v_pk_mul_f32 v[26:27], v[26:27], v[126:127]
	v_pk_mul_f32 v[22:23], v[22:23], v[130:131]
	v_pk_mul_f32 v[18:19], v[18:19], v[134:135]
	v_pk_mul_f32 v[16:17], v[16:17], v[132:133]
	v_pk_mul_f32 v[60:61], v[60:61], v[120:121]
	v_pk_mul_f32 v[56:57], v[56:57], v[124:125]
	v_pk_mul_f32 v[52:53], v[52:53], v[128:129]
	v_pk_mul_f32 v[62:63], v[62:63], v[122:123]
	v_pk_mul_f32 v[58:59], v[58:59], v[126:127]
	v_pk_mul_f32 v[54:55], v[54:55], v[130:131]
	v_pk_mul_f32 v[50:51], v[50:51], v[134:135]
	v_pk_mul_f32 v[48:49], v[48:49], v[132:133]
